# speedup vs baseline: 1.0146x; 1.0146x over previous
; __device__ __forceinline__ float silu_f(float x) { return x * rcpf(1.f + __expf(-x)); }
; __global__ void __launch_bounds__(NTHREADS, 2) fwd_megakernel(Params p_arg) {
;     ...
;       __syncthreads();
;       for (int i = tid; i < 8 * 1024; i += NTHREADS) sc[i] = silu_f(pk->c[i]);
;       __syncthreads();
.LBB0_62:
	s_or_b64 exec, exec, s[10:11]
	s_movk_i32 s4, 0x2000
	v_cmp_gt_i32_e32 vcc, s4, v0
	v_lshlrev_b32_e32 v4, 2, v0
	s_waitcnt lgkmcnt(0)
	s_barrier
	s_and_saveexec_b64 s[4:5], vcc
	s_cbranch_execz .LBB0_65
	s_load_dwordx2 s[12:13], s[8:9], 0x8
	v_ashrrev_i32_e32 v1, 31, v0
	v_add_u32_e32 v5, 0xfffffe00, v0
	s_mov_b64 s[10:11], 0
	s_movk_i32 s14, 0x1dff
	s_waitcnt lgkmcnt(0)
	v_lshl_add_u64 v[2:3], v[0:1], 2, s[12:13]
	s_mov_b64 s[12:13], 0x800
	v_mov_b32_e32 v1, v4
	s_mov_b64 s[12:13], 0x1000
	global_load_dword v6, v[2:3], off
	global_load_dword v7, v[2:3], off offset:2048
	v_lshl_add_u64 v[2:3], v[2:3], 0, s[12:13]
	global_load_dword v8, v[2:3], off
	global_load_dword v9, v[2:3], off offset:2048
	v_lshl_add_u64 v[2:3], v[2:3], 0, s[12:13]
	global_load_dword v10, v[2:3], off
	global_load_dword v11, v[2:3], off offset:2048
	v_lshl_add_u64 v[2:3], v[2:3], 0, s[12:13]
	global_load_dword v12, v[2:3], off
	global_load_dword v13, v[2:3], off offset:2048
	v_lshl_add_u64 v[2:3], v[2:3], 0, s[12:13]
	global_load_dword v14, v[2:3], off
	global_load_dword v15, v[2:3], off offset:2048
	v_lshl_add_u64 v[2:3], v[2:3], 0, s[12:13]
	global_load_dword v16, v[2:3], off
	global_load_dword v17, v[2:3], off offset:2048
	v_lshl_add_u64 v[2:3], v[2:3], 0, s[12:13]
	global_load_dword v18, v[2:3], off
	global_load_dword v19, v[2:3], off offset:2048
	v_lshl_add_u64 v[2:3], v[2:3], 0, s[12:13]
	global_load_dword v20, v[2:3], off
	global_load_dword v21, v[2:3], off offset:2048
	s_waitcnt vmcnt(0)
	v_mul_f32_e32 v22, 0xbfb8aa3b, v6
	v_exp_f32_e32 v22, v22
	s_nop 0
	v_add_f32_e32 v22, 1.0, v22
	v_rcp_f32_e32 v22, v22
	s_nop 0
	v_mul_f32_e32 v6, v6, v22
	ds_write_b32 v1, v6
	v_mul_f32_e32 v22, 0xbfb8aa3b, v7
	v_exp_f32_e32 v22, v22
	s_nop 0
	v_add_f32_e32 v22, 1.0, v22
	v_rcp_f32_e32 v22, v22
	s_nop 0
	v_mul_f32_e32 v7, v7, v22
	ds_write_b32 v1, v7 offset:2048
	v_mul_f32_e32 v22, 0xbfb8aa3b, v8
	v_exp_f32_e32 v22, v22
	s_nop 0
	v_add_f32_e32 v22, 1.0, v22
	v_rcp_f32_e32 v22, v22
	s_nop 0
	v_mul_f32_e32 v8, v8, v22
	ds_write_b32 v1, v8 offset:4096
	v_mul_f32_e32 v22, 0xbfb8aa3b, v9
	v_exp_f32_e32 v22, v22
	s_nop 0
	v_add_f32_e32 v22, 1.0, v22
	v_rcp_f32_e32 v22, v22
	s_nop 0
	v_mul_f32_e32 v9, v9, v22
	ds_write_b32 v1, v9 offset:6144
	v_mul_f32_e32 v22, 0xbfb8aa3b, v10
	v_exp_f32_e32 v22, v22
	s_nop 0
	v_add_f32_e32 v22, 1.0, v22
	v_rcp_f32_e32 v22, v22
	s_nop 0
	v_mul_f32_e32 v10, v10, v22
	ds_write_b32 v1, v10 offset:8192
	v_mul_f32_e32 v22, 0xbfb8aa3b, v11
	v_exp_f32_e32 v22, v22
	s_nop 0
	v_add_f32_e32 v22, 1.0, v22
	v_rcp_f32_e32 v22, v22
	s_nop 0
	v_mul_f32_e32 v11, v11, v22
	ds_write_b32 v1, v11 offset:10240
	v_mul_f32_e32 v22, 0xbfb8aa3b, v12
	v_exp_f32_e32 v22, v22
	s_nop 0
	v_add_f32_e32 v22, 1.0, v22
	v_rcp_f32_e32 v22, v22
	s_nop 0
	v_mul_f32_e32 v12, v12, v22
	ds_write_b32 v1, v12 offset:12288
	v_mul_f32_e32 v22, 0xbfb8aa3b, v13
	v_exp_f32_e32 v22, v22
	s_nop 0
	v_add_f32_e32 v22, 1.0, v22
	v_rcp_f32_e32 v22, v22
	s_nop 0
	v_mul_f32_e32 v13, v13, v22
	ds_write_b32 v1, v13 offset:14336
	v_mul_f32_e32 v22, 0xbfb8aa3b, v14
	v_exp_f32_e32 v22, v22
	s_nop 0
	v_add_f32_e32 v22, 1.0, v22
	v_rcp_f32_e32 v22, v22
	s_nop 0
	v_mul_f32_e32 v14, v14, v22
	ds_write_b32 v1, v14 offset:16384
	v_mul_f32_e32 v22, 0xbfb8aa3b, v15
	v_exp_f32_e32 v22, v22
	s_nop 0
	v_add_f32_e32 v22, 1.0, v22
	v_rcp_f32_e32 v22, v22
	s_nop 0
	v_mul_f32_e32 v15, v15, v22
	ds_write_b32 v1, v15 offset:18432
	v_mul_f32_e32 v22, 0xbfb8aa3b, v16
	v_exp_f32_e32 v22, v22
	s_nop 0
	v_add_f32_e32 v22, 1.0, v22
	v_rcp_f32_e32 v22, v22
	s_nop 0
	v_mul_f32_e32 v16, v16, v22
	ds_write_b32 v1, v16 offset:20480
	v_mul_f32_e32 v22, 0xbfb8aa3b, v17
	v_exp_f32_e32 v22, v22
	s_nop 0
	v_add_f32_e32 v22, 1.0, v22
	v_rcp_f32_e32 v22, v22
	s_nop 0
	v_mul_f32_e32 v17, v17, v22
	ds_write_b32 v1, v17 offset:22528
	v_mul_f32_e32 v22, 0xbfb8aa3b, v18
	v_exp_f32_e32 v22, v22
	s_nop 0
	v_add_f32_e32 v22, 1.0, v22
	v_rcp_f32_e32 v22, v22
	s_nop 0
	v_mul_f32_e32 v18, v18, v22
	ds_write_b32 v1, v18 offset:24576
	v_mul_f32_e32 v22, 0xbfb8aa3b, v19
	v_exp_f32_e32 v22, v22
	s_nop 0
	v_add_f32_e32 v22, 1.0, v22
	v_rcp_f32_e32 v22, v22
	s_nop 0
	v_mul_f32_e32 v19, v19, v22
	ds_write_b32 v1, v19 offset:26624
	v_mul_f32_e32 v22, 0xbfb8aa3b, v20
	v_exp_f32_e32 v22, v22
	s_nop 0
	v_add_f32_e32 v22, 1.0, v22
	v_rcp_f32_e32 v22, v22
	s_nop 0
	v_mul_f32_e32 v20, v20, v22
	ds_write_b32 v1, v20 offset:28672
	v_mul_f32_e32 v22, 0xbfb8aa3b, v21
	v_exp_f32_e32 v22, v22
	s_nop 0
	v_add_f32_e32 v22, 1.0, v22
	v_rcp_f32_e32 v22, v22
	s_nop 0
	v_mul_f32_e32 v21, v21, v22
	ds_write_b32 v1, v21 offset:30720
	v_add_u32_e32 v1, 0x8000, v1
	s_mov_b64 s[10:11], exec

.LBB0_119:
	s_ashr_i32 s5, s4, 31
	s_lshl_b64 s[0:1], s[4:5], 19
	v_lshl_add_u64 v[24:25], v[20:21], 0, s[0:1]
	s_lshl_b64 s[0:1], s[4:5], 18
	v_lshl_add_u64 v[26:27], v[22:23], 0, s[0:1]
	s_ashr_i32 s0, s4, 5
	s_mul_hi_i32 s1, s0, 0x6000
	s_mulk_i32 s0, 0x6000
	s_add_u32 s0, s8, s0
	s_addc_u32 s1, s9, s1
	s_add_u32 s6, s0, 0x1000
	s_addc_u32 s7, s1, 0
	global_load_dwordx4 v[28:31], v[18:19], off
	global_load_dwordx4 v[82:85], v0, s[6:7]
	global_load_dwordx4 v[2:5], v0, s[0:1]
	global_load_dwordx4 v[32:35], v[18:19], off offset:1024
	global_load_dwordx4 v[86:89], v50, s[6:7]
	global_load_dwordx4 v[6:9], v0, s[0:1] offset:1024
	global_load_dwordx4 v[36:39], v[18:19], off offset:2048
	global_load_dwordx4 v[90:93], v51, s[6:7]
	global_load_dwordx4 v[10:13], v0, s[0:1] offset:2048
	global_load_dwordx4 v[40:43], v[18:19], off offset:3072
	global_load_dwordx4 v[94:97], v52, s[6:7]
	global_load_dwordx4 v[14:17], v0, s[0:1] offset:3072
	global_load_dwordx4 v[54:57], v[24:25], off offset:-2048
	global_load_dwordx4 v[58:61], v[24:25], off offset:-1024
	global_load_dwordx4 v[62:65], v[24:25], off
	global_load_dwordx4 v[66:69], v[24:25], off offset:1024
	s_mov_b64 s[6:7], 0
	s_waitcnt vmcnt(4)
	v_pk_add_f32 v[82:83], v[82:83], 1.0 op_sel_hi:[1,0]
	v_pk_add_f32 v[84:85], v[84:85], 1.0 op_sel_hi:[1,0]
	v_pk_add_f32 v[86:87], v[86:87], 1.0 op_sel_hi:[1,0]
	v_pk_add_f32 v[88:89], v[88:89], 1.0 op_sel_hi:[1,0]
	v_pk_add_f32 v[90:91], v[90:91], 1.0 op_sel_hi:[1,0]
	v_pk_add_f32 v[92:93], v[92:93], 1.0 op_sel_hi:[1,0]
	v_pk_add_f32 v[94:95], v[94:95], 1.0 op_sel_hi:[1,0]
	v_pk_add_f32 v[96:97], v[96:97], 1.0 op_sel_hi:[1,0]
	v_pk_mul_f32 v[28:29], v[28:29], v[82:83]
	v_pk_mul_f32 v[30:31], v[30:31], v[84:85]
	v_pk_mul_f32 v[32:33], v[32:33], v[86:87]
	v_pk_mul_f32 v[34:35], v[34:35], v[88:89]
	v_pk_mul_f32 v[36:37], v[36:37], v[90:91]
	v_pk_mul_f32 v[38:39], v[38:39], v[92:93]
	v_pk_mul_f32 v[40:41], v[40:41], v[94:95]
	v_pk_mul_f32 v[42:43], v[42:43], v[96:97]
.Lnl1_A:
	v_lshl_add_u64 v[24:25], v[24:25], 0, s[48:49]
	global_load_dwordx4 v[82:85], v[24:25], off offset:-2048
	global_load_dwordx4 v[86:89], v[24:25], off offset:-1024
	global_load_dwordx4 v[90:93], v[24:25], off
	global_load_dwordx4 v[94:97], v[24:25], off offset:1024
	v_lshl_add_u64 v[70:71], v[26:27], 0, s[6:7]
	s_cmp_eq_u32 s6, 0
	s_cbranch_scc0 .Lnl1_A8
	s_waitcnt vmcnt(4)
	s_branch .Lnl1_Ago
.Lnl1_A8:
	s_waitcnt vmcnt(8)
.Lnl1_Ago:
	v_mov_b32_e32 v80, v55
	v_mov_b32_e32 v81, v59
	v_mov_b32_e32 v78, v54
	v_mov_b32_e32 v79, v58
	v_pk_mul_f32 v[80:81], v[80:81], v[80:81]
	v_mov_b32_e32 v74, v56
	v_mov_b32_e32 v75, v60
	v_pk_fma_f32 v[78:79], v[78:79], v[78:79], v[80:81]
	v_mov_b32_e32 v76, v57
	v_mov_b32_e32 v77, v61
	v_pk_fma_f32 v[74:75], v[74:75], v[74:75], v[78:79]
	s_nop 0
	v_pk_fma_f32 v[72:73], v[76:77], v[76:77], v[74:75]
	s_nop 0
	v_add_f32_e32 v53, v72, v73
	v_mov_b32_e32 v80, v63
	v_mov_b32_e32 v81, v67
	v_mov_b32_e32 v78, v62
	v_mov_b32_e32 v79, v66
	v_pk_mul_f32 v[80:81], v[80:81], v[80:81]
	v_mov_b32_e32 v74, v64
	v_mov_b32_e32 v75, v68
	v_pk_fma_f32 v[78:79], v[78:79], v[78:79], v[80:81]
	v_mov_b32_e32 v76, v65
	v_mov_b32_e32 v77, v69
	v_pk_fma_f32 v[74:75], v[74:75], v[74:75], v[78:79]
	s_nop 0
	v_pk_fma_f32 v[74:75], v[76:77], v[76:77], v[74:75]
	s_nop 0
	v_add_f32_e32 v53, v53, v74
	v_add_f32_e32 v53, v53, v75
	ds_bpermute_b32 v72, v44, v53
	s_waitcnt lgkmcnt(0)
	v_add_f32_e32 v53, v53, v72
	ds_bpermute_b32 v72, v45, v53
	s_waitcnt lgkmcnt(0)
	v_add_f32_e32 v53, v53, v72
	ds_bpermute_b32 v72, v46, v53
	s_waitcnt lgkmcnt(0)
	v_add_f32_e32 v53, v53, v72
	ds_bpermute_b32 v72, v47, v53
	s_waitcnt lgkmcnt(0)
	v_add_f32_e32 v53, v53, v72
	ds_bpermute_b32 v72, v48, v53
	s_waitcnt lgkmcnt(0)
	v_add_f32_e32 v53, v53, v72
	ds_bpermute_b32 v72, v49, v53
	s_waitcnt lgkmcnt(0)
	v_add_f32_e32 v53, v53, v72
	v_fmamk_f32 v53, v53, 0x3a800000, v149
	v_cmp_gt_f32_e32 vcc, s26, v53
	v_mul_f32_e32 v72, 0x4b800000, v53
	s_nop 0
	v_cndmask_b32_e32 v53, v53, v72, vcc
	v_rsq_f32_e32 v53, v53
	s_nop 0
	v_mul_f32_e32 v72, 0x45800000, v53
	v_cndmask_b32_e32 v72, v53, v72, vcc
	v_pk_mul_f32 v[54:55], v[72:73], v[54:55] op_sel_hi:[0,1]
	v_pk_mul_f32 v[56:57], v[72:73], v[56:57] op_sel_hi:[0,1]
	v_pk_fma_f32 v[54:55], v[54:55], v[28:29], v[2:3]
	v_pk_fma_f32 v[56:57], v[56:57], v[30:31], v[4:5]
	v_cvt_pk_bf16_f32 v54, v54, v55
	v_cvt_pk_bf16_f32 v55, v56, v57
	global_store_dwordx2 v[70:71], v[54:55], off offset:-1024
	v_pk_mul_f32 v[54:55], v[72:73], v[58:59] op_sel_hi:[0,1]
	v_pk_mul_f32 v[56:57], v[72:73], v[60:61] op_sel_hi:[0,1]
	v_pk_fma_f32 v[54:55], v[54:55], v[32:33], v[6:7]
	v_pk_fma_f32 v[56:57], v[56:57], v[34:35], v[8:9]
	v_cvt_pk_bf16_f32 v54, v54, v55
	v_cvt_pk_bf16_f32 v55, v56, v57
	global_store_dwordx2 v[70:71], v[54:55], off offset:-512
	v_pk_mul_f32 v[54:55], v[72:73], v[62:63] op_sel_hi:[0,1]
	v_pk_mul_f32 v[56:57], v[72:73], v[64:65] op_sel_hi:[0,1]
	v_pk_fma_f32 v[54:55], v[54:55], v[36:37], v[10:11]
	v_pk_fma_f32 v[56:57], v[56:57], v[38:39], v[12:13]
	v_cvt_pk_bf16_f32 v54, v54, v55
	v_cvt_pk_bf16_f32 v55, v56, v57
	global_store_dwordx2 v[70:71], v[54:55], off
	v_pk_mul_f32 v[54:55], v[72:73], v[66:67] op_sel_hi:[0,1]
	v_pk_mul_f32 v[56:57], v[72:73], v[68:69] op_sel_hi:[0,1]
	v_pk_fma_f32 v[54:55], v[54:55], v[40:41], v[14:15]
	v_pk_fma_f32 v[56:57], v[56:57], v[42:43], v[16:17]
	v_cvt_pk_bf16_f32 v54, v54, v55
	v_cvt_pk_bf16_f32 v55, v56, v57
	global_store_dwordx2 v[70:71], v[54:55], off offset:512
	s_add_u32 s6, s6, 0x800
	s_addc_u32 s7, s7, 0
	v_lshl_add_u64 v[70:71], v[26:27], 0, s[6:7]
	s_cmpk_eq_u32 s6, 0x7800
	s_cbranch_scc1 .Lnl1_Blast
	v_lshl_add_u64 v[24:25], v[24:25], 0, s[48:49]
	global_load_dwordx4 v[54:57], v[24:25], off offset:-2048
	global_load_dwordx4 v[58:61], v[24:25], off offset:-1024
	global_load_dwordx4 v[62:65], v[24:25], off
	global_load_dwordx4 v[66:69], v[24:25], off offset:1024
	s_waitcnt vmcnt(8)
	s_branch .Lnl1_Bgo
.Lnl1_Blast:
	s_waitcnt vmcnt(4)
.Lnl1_Bgo:
	v_mov_b32_e32 v80, v83
	v_mov_b32_e32 v81, v87
	v_mov_b32_e32 v78, v82
	v_mov_b32_e32 v79, v86
	v_pk_mul_f32 v[80:81], v[80:81], v[80:81]
	v_mov_b32_e32 v74, v84
	v_mov_b32_e32 v75, v88
	v_pk_fma_f32 v[78:79], v[78:79], v[78:79], v[80:81]
	v_mov_b32_e32 v76, v85
	v_mov_b32_e32 v77, v89
	v_pk_fma_f32 v[74:75], v[74:75], v[74:75], v[78:79]
	s_nop 0
	v_pk_fma_f32 v[72:73], v[76:77], v[76:77], v[74:75]
	s_nop 0
	v_add_f32_e32 v53, v72, v73
	v_mov_b32_e32 v80, v91
	v_mov_b32_e32 v81, v95
	v_mov_b32_e32 v78, v90
	v_mov_b32_e32 v79, v94
	v_pk_mul_f32 v[80:81], v[80:81], v[80:81]
	v_mov_b32_e32 v74, v92
	v_mov_b32_e32 v75, v96
	v_pk_fma_f32 v[78:79], v[78:79], v[78:79], v[80:81]
	v_mov_b32_e32 v76, v93
	v_mov_b32_e32 v77, v97
	v_pk_fma_f32 v[74:75], v[74:75], v[74:75], v[78:79]
	s_nop 0
	v_pk_fma_f32 v[74:75], v[76:77], v[76:77], v[74:75]
	s_nop 0
	v_add_f32_e32 v53, v53, v74
	v_add_f32_e32 v53, v53, v75
	ds_bpermute_b32 v72, v44, v53
	s_waitcnt lgkmcnt(0)
	v_add_f32_e32 v53, v53, v72
	ds_bpermute_b32 v72, v45, v53
	s_waitcnt lgkmcnt(0)
	v_add_f32_e32 v53, v53, v72
	ds_bpermute_b32 v72, v46, v53
	s_waitcnt lgkmcnt(0)
	v_add_f32_e32 v53, v53, v72
	ds_bpermute_b32 v72, v47, v53
	s_waitcnt lgkmcnt(0)
	v_add_f32_e32 v53, v53, v72
	ds_bpermute_b32 v72, v48, v53
	s_waitcnt lgkmcnt(0)
	v_add_f32_e32 v53, v53, v72
	ds_bpermute_b32 v72, v49, v53
	s_waitcnt lgkmcnt(0)
	v_add_f32_e32 v53, v53, v72
	v_fmamk_f32 v53, v53, 0x3a800000, v149
	v_cmp_gt_f32_e32 vcc, s26, v53
	v_mul_f32_e32 v72, 0x4b800000, v53
	s_nop 0
	v_cndmask_b32_e32 v53, v53, v72, vcc
	v_rsq_f32_e32 v53, v53
	s_nop 0
	v_mul_f32_e32 v72, 0x45800000, v53
	v_cndmask_b32_e32 v72, v53, v72, vcc
	v_pk_mul_f32 v[82:83], v[72:73], v[82:83] op_sel_hi:[0,1]
	v_pk_mul_f32 v[84:85], v[72:73], v[84:85] op_sel_hi:[0,1]
	v_pk_fma_f32 v[82:83], v[82:83], v[28:29], v[2:3]
	v_pk_fma_f32 v[84:85], v[84:85], v[30:31], v[4:5]
	v_cvt_pk_bf16_f32 v82, v82, v83
	v_cvt_pk_bf16_f32 v83, v84, v85
	global_store_dwordx2 v[70:71], v[82:83], off offset:-1024
	v_pk_mul_f32 v[82:83], v[72:73], v[86:87] op_sel_hi:[0,1]
	v_pk_mul_f32 v[84:85], v[72:73], v[88:89] op_sel_hi:[0,1]
	v_pk_fma_f32 v[82:83], v[82:83], v[32:33], v[6:7]
	v_pk_fma_f32 v[84:85], v[84:85], v[34:35], v[8:9]
	v_cvt_pk_bf16_f32 v82, v82, v83
	v_cvt_pk_bf16_f32 v83, v84, v85
	global_store_dwordx2 v[70:71], v[82:83], off offset:-512
	v_pk_mul_f32 v[82:83], v[72:73], v[90:91] op_sel_hi:[0,1]
	v_pk_mul_f32 v[84:85], v[72:73], v[92:93] op_sel_hi:[0,1]
	v_pk_fma_f32 v[82:83], v[82:83], v[36:37], v[10:11]
	v_pk_fma_f32 v[84:85], v[84:85], v[38:39], v[12:13]
	v_cvt_pk_bf16_f32 v82, v82, v83
	v_cvt_pk_bf16_f32 v83, v84, v85
	global_store_dwordx2 v[70:71], v[82:83], off
	v_pk_mul_f32 v[82:83], v[72:73], v[94:95] op_sel_hi:[0,1]
	v_pk_mul_f32 v[84:85], v[72:73], v[96:97] op_sel_hi:[0,1]
	v_pk_fma_f32 v[82:83], v[82:83], v[40:41], v[14:15]
	v_pk_fma_f32 v[84:85], v[84:85], v[42:43], v[16:17]
	v_cvt_pk_bf16_f32 v82, v82, v83
	v_cvt_pk_bf16_f32 v83, v84, v85
	global_store_dwordx2 v[70:71], v[82:83], off offset:512
	s_add_u32 s6, s6, 0x800
	s_addc_u32 s7, s7, 0
	s_cmpk_eq_u32 s6, 0x8000
	s_cbranch_scc0 .Lnl1_A
	s_add_i32 s4, s4, s3
	s_cmpk_gt_i32 s4, 0xff
	s_cbranch_scc0 .LBB0_119

; __device__ __forceinline__ float bf2f(u16 v) { return __uint_as_float(((uint32_t)v) << 16); }
; __device__ __forceinline__ u16 f2bf(float a) { return (u16)(pack2(a, 0.f) & 0xffffu); }
; __global__ void __launch_bounds__(NTHREADS, 2) fwd_megakernel(Params p_arg) {
;     ...
; #pragma unroll 2
;           for (int itr = 0; itr < 16; ++itr) {
;             const int s = itr * 8 + (lane >> 3);
;             const size_t tok = tok0 + s;
;             uint4 raw = *(const uint4*)(ZVp + tok * 512 + g * 64 + c0);
;             float4 p0 = *(const float4*)(VSS + tok * 8), p1 = *(const float4*)(VSS + tok * 8 + 4);
;             float ssum = p0.x + p0.y + p0.z + p0.w + p1.x + p1.y + p1.z + p1.w;
;             float rs = rsqrtf(ssum * (1.f / 512.f) + EPS);
;             uint32_t wv[4] = {raw.x, raw.y, raw.z, raw.w};
; #pragma unroll
;             for (int i = 0; i < 8; ++i) {
;               u16 e = (u16)((i & 1) ? (wv[i >> 1] >> 16) : (wv[i >> 1] & 0xffffu));
;               vT[(c0 + i) * 136 + s] = f2bf(bf2f(e) * rs * gv[i]);
;             }
;           }
.LBB0_294:
	global_load_dwordx4 v[2:5], v[76:77], off
	global_load_dwordx4 v[6:9], v[76:77], off offset:16
	s_ashr_i32 s10, s99, 5
	s_ashr_i32 s11, s10, 31
	s_and_b32 s1, s98, 31
	s_lshl_b64 s[36:37], s[10:11], 12
	s_lshl_b32 s0, s1, 7
	v_or_b32_e32 v0, s36, v82
	s_lshl_b32 s14, s1, 12
	s_lshl_b32 s1, s1, 17
	v_mov_b32_e32 v11, s37
	v_or_b32_e32 v10, s0, v0
	s_lshl_b64 s[12:13], s[10:11], 17
	s_lshl_b64 s[10:11], s[10:11], 22
	v_lshlrev_b64 v[10:11], 10, v[10:11]
	s_or_b32 s12, s12, s14
	s_or_b32 s10, s10, s1
	v_lshl_add_u64 v[10:11], v[80:81], 0, v[10:11]
	v_lshl_add_u64 v[12:13], v[84:85], 0, s[12:13]
	v_lshl_add_u64 v[14:15], v[86:87], 0, s[10:11]
	s_mov_b64 s[10:11], 0
	v_mov_b32_e32 v0, v130
	v_lshl_add_u64 v[28:29], v[12:13], 0, s[10:11]
	s_mov_b64 s[12:13], 0x71c0000
	v_lshl_add_u64 v[30:31], v[28:29], 0, s[12:13]
	v_lshl_add_u64 v[28:29], v[10:11], 0, s[34:35]
	global_load_dwordx4 v[200:203], v[28:29], off
	s_nop 0
	global_load_dwordx4 v[204:207], v[30:31], off
	s_nop 0
	global_load_dwordx4 v[208:211], v[30:31], off offset:16
	v_lshl_add_u64 v[28:29], v[14:15], 0, s[34:35]
	global_load_dwordx4 v[212:215], v[28:29], off offset:-8
	s_nop 0
	global_load_dwordx4 v[216:219], v[30:31], off offset:256
	s_nop 0
	global_load_dwordx4 v[220:223], v[30:31], off offset:272
.Lmxa_loop:
	s_waitcnt vmcnt(0)
	v_mov_b32_e32 v16, v200
	v_mov_b32_e32 v17, v201
	v_mov_b32_e32 v18, v202
	v_mov_b32_e32 v19, v203
	v_mov_b32_e32 v20, v204
	v_mov_b32_e32 v21, v205
	v_mov_b32_e32 v22, v206
	v_mov_b32_e32 v23, v207
	v_mov_b32_e32 v24, v208
	v_mov_b32_e32 v25, v209
	v_mov_b32_e32 v26, v210
	v_mov_b32_e32 v27, v211
	v_mov_b32_e32 v224, v212
	v_mov_b32_e32 v225, v213
	v_mov_b32_e32 v226, v214
	v_mov_b32_e32 v227, v215
	v_mov_b32_e32 v228, v216
	v_mov_b32_e32 v229, v217
	v_mov_b32_e32 v230, v218
	v_mov_b32_e32 v231, v219
	v_mov_b32_e32 v232, v220
	v_mov_b32_e32 v233, v221
	v_mov_b32_e32 v234, v222
	v_mov_b32_e32 v235, v223
	s_add_u32 s10, s10, 0x200
	s_addc_u32 s11, s11, 0
	v_lshl_add_u64 v[10:11], v[10:11], 0, s[94:95]
	v_lshl_add_u64 v[14:15], v[14:15], 0, s[94:95]
	s_cmpk_eq_i32 s10, 0x1000
	s_cbranch_scc1 .Lmxa_nopf
	v_lshl_add_u64 v[28:29], v[12:13], 0, s[10:11]
	s_mov_b64 s[12:13], 0x71c0000
	v_lshl_add_u64 v[30:31], v[28:29], 0, s[12:13]
	v_lshl_add_u64 v[28:29], v[10:11], 0, s[34:35]
	global_load_dwordx4 v[200:203], v[28:29], off
	s_nop 0
	global_load_dwordx4 v[204:207], v[30:31], off
	s_nop 0
	global_load_dwordx4 v[208:211], v[30:31], off offset:16
	v_lshl_add_u64 v[28:29], v[14:15], 0, s[34:35]
	global_load_dwordx4 v[212:215], v[28:29], off offset:-8
	s_nop 0
	global_load_dwordx4 v[216:219], v[30:31], off offset:256
	s_nop 0
	global_load_dwordx4 v[220:223], v[30:31], off offset:272
; __device__ __forceinline__ float bf2f(u16 v) { return __uint_as_float(((uint32_t)v) << 16); }
; __device__ __forceinline__ u16 f2bf(float a) { return (u16)(pack2(a, 0.f) & 0xffffu); }
; __global__ void __launch_bounds__(NTHREADS, 2) fwd_megakernel(Params p_arg) {
;     ...
;           for (int itr = 0; itr < 16; ++itr) {
;             const int s = itr * 8 + (lane >> 3);
;             const size_t tok = tok0 + s;
;             uint4 raw = *(const uint4*)(ZVp + tok * 512 + g * 64 + c0);
;             float4 p0 = *(const float4*)(VSS + tok * 8), p1 = *(const float4*)(VSS + tok * 8 + 4);
;             float ssum = p0.x + p0.y + p0.z + p0.w + p1.x + p1.y + p1.z + p1.w;
;             float rs = rsqrtf(ssum * (1.f / 512.f) + EPS);
;             uint32_t wv[4] = {raw.x, raw.y, raw.z, raw.w};
; #pragma unroll
;             for (int i = 0; i < 8; ++i) {
;               u16 e = (u16)((i & 1) ? (wv[i >> 1] >> 16) : (wv[i >> 1] & 0xffffu));
;               vT[(c0 + i) * 136 + s] = f2bf(bf2f(e) * rs * gv[i]);
;             }
;           }
;         }
;         __syncthreads();
;         bf16x8 vf[4][4];
; #pragma unroll
;         for (int ct = 0; ct < 4; ++ct)
; #pragma unroll
;           for (int ks = 0; ks < 4; ++ks) vf[ct][ks] = *(const bf16x8*)(vT + (ct * 16 + fr) * 136 + ks * 32 + fq * 8);
;         const u16* wsb = wl + WOFF_S + (size_t)g * 128 * 128;
.Lmxa_nopf:
	v_add_f32_e32 v20, v20, v21
	v_add_f32_e32 v20, v20, v22
	v_add_f32_e32 v20, v20, v23
	v_add_f32_e32 v20, v20, v24
	v_add_f32_e32 v20, v20, v25
	v_add_f32_e32 v20, v20, v26
	v_add_f32_e32 v20, v20, v27
	v_fmamk_f32 v20, v20, 0x3b000000, v149
	v_cmp_gt_f32_e32 vcc, s26, v20
	v_mul_f32_e32 v21, 0x4b800000, v20
	s_nop 0
	v_cndmask_b32_e32 v20, v20, v21, vcc
	v_rsq_f32_e32 v20, v20
	s_nop 0
	v_mul_f32_e32 v21, 0x45800000, v20
	v_cndmask_b32_e32 v20, v20, v21, vcc
	v_lshlrev_b32_e32 v21, 16, v16
	v_and_b32_e32 v16, 0xffff0000, v16
	v_mul_f32_e32 v16, v20, v16
	v_mul_f32_e32 v16, v3, v16
	v_cvt_pk_bf16_f32 v16, v16, s0
	ds_write_b16 v0, v16 offset:272
	v_lshlrev_b32_e32 v16, 16, v17
	v_mul_f32_e32 v16, v20, v16
	v_mul_f32_e32 v16, v4, v16
	v_cvt_pk_bf16_f32 v16, v16, s0
	ds_write_b16 v0, v16 offset:544
	v_and_b32_e32 v16, 0xffff0000, v17
	v_mul_f32_e32 v16, v20, v16
	v_mul_f32_e32 v16, v5, v16
	v_cvt_pk_bf16_f32 v16, v16, s0
	ds_write_b16 v0, v16 offset:816
	v_lshlrev_b32_e32 v16, 16, v18
	v_mul_f32_e32 v16, v20, v16
	v_mul_f32_e32 v16, v6, v16
	v_cvt_pk_bf16_f32 v16, v16, s0
	ds_write_b16 v0, v16 offset:1088
	v_and_b32_e32 v16, 0xffff0000, v18
	v_mul_f32_e32 v16, v20, v16
	v_mul_f32_e32 v16, v7, v16
	v_cvt_pk_bf16_f32 v16, v16, s0
	ds_write_b16 v0, v16 offset:1360
	v_lshlrev_b32_e32 v16, 16, v19
	v_mul_f32_e32 v16, v20, v16
	v_mul_f32_e32 v16, v8, v16
	v_cvt_pk_bf16_f32 v16, v16, s0
	ds_write_b16 v0, v16 offset:1632
	v_and_b32_e32 v16, 0xffff0000, v19
	v_mul_f32_e32 v21, v20, v21
	v_mul_f32_e32 v16, v20, v16
	v_mul_f32_e32 v21, v2, v21
	v_mul_f32_e32 v16, v9, v16
	v_cvt_pk_bf16_f32 v21, v21, s0
	v_cvt_pk_bf16_f32 v16, v16, s0
	ds_write_b16 v0, v21
	ds_write_b16 v0, v16 offset:1904
	v_mov_b32_e32 v16, v224
	v_mov_b32_e32 v17, v225
	v_mov_b32_e32 v18, v226
	v_mov_b32_e32 v19, v227
	v_mov_b32_e32 v20, v228
	v_mov_b32_e32 v21, v229
	v_mov_b32_e32 v22, v230
	v_mov_b32_e32 v23, v231
	v_mov_b32_e32 v24, v232
	v_mov_b32_e32 v25, v233
	v_mov_b32_e32 v26, v234
	v_mov_b32_e32 v27, v235
	v_add_f32_e32 v20, v20, v21
	v_add_f32_e32 v20, v20, v22
	v_add_f32_e32 v20, v20, v23
	v_add_f32_e32 v20, v20, v24
	v_add_f32_e32 v20, v20, v25
	v_add_f32_e32 v20, v20, v26
	v_add_f32_e32 v20, v20, v27
	v_fmamk_f32 v20, v20, 0x3b000000, v149
	v_cmp_gt_f32_e32 vcc, s26, v20
	v_mul_f32_e32 v21, 0x4b800000, v20
	s_nop 0
	v_cndmask_b32_e32 v20, v20, v21, vcc
	v_rsq_f32_e32 v20, v20
	s_nop 0
	v_mul_f32_e32 v21, 0x45800000, v20
	v_cndmask_b32_e32 v20, v20, v21, vcc
	v_lshlrev_b32_e32 v21, 16, v16
	v_and_b32_e32 v16, 0xffff0000, v16
	v_mul_f32_e32 v16, v20, v16
	v_mul_f32_e32 v16, v3, v16
	v_cvt_pk_bf16_f32 v16, v16, s0
	ds_write_b16 v0, v16 offset:288
	v_lshlrev_b32_e32 v16, 16, v17
	v_mul_f32_e32 v16, v20, v16
	v_mul_f32_e32 v16, v4, v16
	v_cvt_pk_bf16_f32 v16, v16, s0
	ds_write_b16 v0, v16 offset:560
	v_and_b32_e32 v16, 0xffff0000, v17
	v_mul_f32_e32 v16, v20, v16
	v_mul_f32_e32 v16, v5, v16
	v_cvt_pk_bf16_f32 v16, v16, s0
	ds_write_b16 v0, v16 offset:832
	v_lshlrev_b32_e32 v16, 16, v18
	v_mul_f32_e32 v16, v20, v16
	v_mul_f32_e32 v16, v6, v16
	v_cvt_pk_bf16_f32 v16, v16, s0
	ds_write_b16 v0, v16 offset:1104
	v_and_b32_e32 v16, 0xffff0000, v18
	v_mul_f32_e32 v16, v20, v16
	v_mul_f32_e32 v16, v7, v16
	v_cvt_pk_bf16_f32 v16, v16, s0
	ds_write_b16 v0, v16 offset:1376
	v_lshlrev_b32_e32 v16, 16, v19
	v_mul_f32_e32 v16, v20, v16
	v_mul_f32_e32 v16, v8, v16
	v_cvt_pk_bf16_f32 v16, v16, s0
	ds_write_b16 v0, v16 offset:1648
	v_and_b32_e32 v16, 0xffff0000, v19
	v_mul_f32_e32 v21, v20, v21
	v_mul_f32_e32 v16, v20, v16
	v_mul_f32_e32 v21, v2, v21
	v_mul_f32_e32 v16, v9, v16
	v_cvt_pk_bf16_f32 v21, v21, s0
	v_cvt_pk_bf16_f32 v16, v16, s0
	ds_write_b16 v0, v21 offset:16
	ds_write_b16 v0, v16 offset:1920
	v_add_u32_e32 v0, 32, v0
	s_cmpk_eq_i32 s10, 0x1000
	s_cbranch_scc0 .Lmxa_loop
	s_waitcnt lgkmcnt(0)
	s_barrier
	ds_read_b128 v[2:5], v131
	ds_read_b128 v[6:9], v131 offset:64
	ds_read_b128 v[10:13], v131 offset:128
	ds_read_b128 v[14:17], v131 offset:192
	ds_read_b128 v[18:21], v131 offset:4352
	ds_read_b128 v[22:25], v131 offset:4416
	ds_read_b128 v[26:29], v131 offset:4480
	ds_read_b128 v[30:33], v131 offset:4544
	ds_read_b128 v[34:37], v131 offset:8704
	ds_read_b128 v[38:41], v131 offset:8768
	ds_read_b128 v[42:45], v131 offset:8832
	ds_read_b128 v[46:49], v131 offset:8896
	ds_read_b128 v[50:53], v131 offset:13056
	ds_read_b128 v[54:57], v131 offset:13120
	ds_read_b128 v[58:61], v131 offset:13184
	ds_read_b128 v[62:65], v131 offset:13248
	s_add_u32 s10, s0, s36
	s_addc_u32 s11, 0, s37
	v_lshl_add_u64 v[68:69], s[10:11], 0, v[74:75]
	v_lshlrev_b64 v[66:67], 10, v[68:69]
	v_lshlrev_b64 v[68:69], 11, v[68:69]
	v_lshl_add_u64 v[66:67], v[92:93], 0, v[66:67]
	v_lshl_add_u64 v[68:69], v[94:95], 0, v[68:69]
	s_mov_b64 s[10:11], 0
	v_mov_b64_e32 v[70:71], v[90:91]

; __global__ void __launch_bounds__(NTHREADS, 2) fwd_megakernel(Params p_arg) {
;     ...
;         for (int g = 0; g < 4; ++g) {
;           const int h = kvh * 4 + g;
;           const size_t tokq = tok0 + qt * 16 + fr;
;           bf16x8 qf[2];
;           qf[0] = *(const bf16x8*)(ZQp + tokq * 512 + h * 64 + fq * 8);
;           qf[1] = *(const bf16x8*)(ZQp + tokq * 512 + h * 64 + 32 + fq * 8);
.LBB0_311:
	s_or_b64 exec, exec, s[14:15]
	s_lshl_b32 s0, s28, 2
	s_xor_b64 s[92:93], s[12:13], -1
	s_or_b32 s0, s0, 1
	s_lshl_b64 s[12:13], s[28:29], 4
	s_add_u32 s12, s45, s12
	s_addc_u32 s13, s46, s13
	s_lshl_b64 s[14:15], s[28:29], 9
	v_lshl_add_u64 v[108:109], v[102:103], 0, s[14:15]
	v_lshl_add_u64 v[110:111], v[104:105], 0, s[14:15]
	s_mov_b64 s[24:25], 0
	global_load_dwordx4 v[200:203], v[108:109], off offset:-64
	global_load_dwordx4 v[204:207], v[108:109], off
	s_waitcnt lgkmcnt(0)
	s_barrier
.LBB0_312:
	s_cmp_eq_u32 s24, 0
	s_cbranch_scc1 .Lq_first
	s_waitcnt vmcnt(2)
	s_branch .Lq_go

; __global__ void __launch_bounds__(NTHREADS, 2) fwd_megakernel(Params p_arg) {
;     ...
;           const int h = kvh * 4 + g;
;           const size_t tokq = tok0 + qt * 16 + fr;
;           bf16x8 qf[2];
;           qf[0] = *(const bf16x8*)(ZQp + tokq * 512 + h * 64 + fq * 8);
;           qf[1] = *(const bf16x8*)(ZQp + tokq * 512 + h * 64 + 32 + fq * 8);
;           f32x4 S[18];
; #pragma unroll
;           for (int i = 0; i < 18; ++i) {
;             S[i] = f32x4{0.f, 0.f, 0.f, 0.f};
; #pragma unroll
;             for (int ks = 0; ks < 2; ++ks) {
;               bf16x8 kf = *(const bf16x8*)(Ks + ((kt0 + i) * 16 + fr) * 72 + ks * 32 + fq * 8);
;               S[i] = __builtin_amdgcn_mfma_f32_16x16x32_bf16(kf, qf[ks], S[i], 0, 0, 0);
;             }
;             if ((i % 3) == 2) __builtin_amdgcn_sched_barrier(0);
;           }
.Lq_go:
	v_mov_b32_e32 v2, v200
	v_mov_b32_e32 v3, v201
	v_mov_b32_e32 v4, v202
	v_mov_b32_e32 v5, v203
	v_mov_b32_e32 v156, v204
	v_mov_b32_e32 v157, v205
	v_mov_b32_e32 v158, v206
	v_mov_b32_e32 v159, v207
	v_lshl_add_u64 v[6:7], v[108:109], 0, s[24:25]
	global_load_dwordx4 v[200:203], v[6:7], off offset:64
	global_load_dwordx4 v[204:207], v[6:7], off offset:128
	ds_read_b128 v[6:9], v133
	ds_read_b128 v[10:13], v133 offset:64
	s_waitcnt lgkmcnt(1)
	v_mfma_f32_16x16x32_bf16 v[6:9], v[6:9], v[2:5], 0
	s_waitcnt lgkmcnt(0)
	v_mfma_f32_16x16x32_bf16 v[70:73], v[10:13], v[156:159], v[6:9]
	ds_read_b128 v[10:13], v134 offset:64
	s_nop 4
	ds_read_b128 v[6:9], v134
	s_waitcnt lgkmcnt(0)
	v_mfma_f32_16x16x32_bf16 v[6:9], v[6:9], v[2:5], 0
	v_mfma_f32_16x16x32_bf16 v[66:69], v[10:13], v[156:159], v[6:9]
	ds_read_b128 v[10:13], v135 offset:64
	s_nop 5
	ds_read_b128 v[6:9], v135
	s_waitcnt lgkmcnt(0)
	v_mfma_f32_16x16x32_bf16 v[6:9], v[6:9], v[2:5], 0
	v_mfma_f32_16x16x32_bf16 v[62:65], v[10:13], v[156:159], v[6:9]
	s_nop 6
	ds_read_b128 v[6:9], v136
	ds_read_b128 v[10:13], v136 offset:64
	ds_read_b128 v[14:17], v137
	ds_read_b128 v[18:21], v137 offset:64
	s_waitcnt lgkmcnt(3)
	v_mfma_f32_16x16x32_bf16 v[6:9], v[6:9], v[2:5], 0
	s_waitcnt lgkmcnt(2)
	v_mfma_f32_16x16x32_bf16 v[58:61], v[10:13], v[156:159], v[6:9]
	ds_read_b128 v[10:13], v138 offset:64
	s_nop 4
	ds_read_b128 v[6:9], v138
	s_waitcnt lgkmcnt(3)
	v_mfma_f32_16x16x32_bf16 v[14:17], v[14:17], v[2:5], 0
	s_waitcnt lgkmcnt(0)
	v_mfma_f32_16x16x32_bf16 v[6:9], v[6:9], v[2:5], 0
	v_mfma_f32_16x16x32_bf16 v[54:57], v[18:21], v[156:159], v[14:17]
	v_mfma_f32_16x16x32_bf16 v[50:53], v[10:13], v[156:159], v[6:9]
	s_nop 5
	ds_read_b128 v[6:9], v139
	ds_read_b128 v[10:13], v139 offset:64
	ds_read_b128 v[14:17], v140
	ds_read_b128 v[18:21], v140 offset:64
	s_waitcnt lgkmcnt(3)
	v_mfma_f32_16x16x32_bf16 v[6:9], v[6:9], v[2:5], 0
	s_waitcnt lgkmcnt(2)
	v_mfma_f32_16x16x32_bf16 v[46:49], v[10:13], v[156:159], v[6:9]
	ds_read_b128 v[10:13], v141 offset:64
	s_nop 4
	ds_read_b128 v[6:9], v141
	s_waitcnt lgkmcnt(3)
	v_mfma_f32_16x16x32_bf16 v[14:17], v[14:17], v[2:5], 0
	s_waitcnt lgkmcnt(0)
	v_mfma_f32_16x16x32_bf16 v[6:9], v[6:9], v[2:5], 0
	v_mfma_f32_16x16x32_bf16 v[42:45], v[18:21], v[156:159], v[14:17]
	v_mfma_f32_16x16x32_bf16 v[38:41], v[10:13], v[156:159], v[6:9]
	s_nop 5
	ds_read_b128 v[6:9], v142
	ds_read_b128 v[10:13], v142 offset:64
	ds_read_b128 v[14:17], v143
	ds_read_b128 v[18:21], v143 offset:64
	s_waitcnt lgkmcnt(3)
	v_mfma_f32_16x16x32_bf16 v[6:9], v[6:9], v[2:5], 0
	s_waitcnt lgkmcnt(2)
	v_mfma_f32_16x16x32_bf16 v[34:37], v[10:13], v[156:159], v[6:9]
	ds_read_b128 v[10:13], v144 offset:64
	s_nop 4
	ds_read_b128 v[6:9], v144
	s_waitcnt lgkmcnt(3)
	v_mfma_f32_16x16x32_bf16 v[14:17], v[14:17], v[2:5], 0
	s_waitcnt lgkmcnt(0)
	v_mfma_f32_16x16x32_bf16 v[6:9], v[6:9], v[2:5], 0
	v_mfma_f32_16x16x32_bf16 v[30:33], v[18:21], v[156:159], v[14:17]
	v_mfma_f32_16x16x32_bf16 v[26:29], v[10:13], v[156:159], v[6:9]
	s_nop 5
	ds_read_b128 v[6:9], v145
	ds_read_b128 v[10:13], v145 offset:64
	ds_read_b128 v[14:17], v146
	ds_read_b128 v[18:21], v146 offset:64
	s_waitcnt lgkmcnt(3)
	v_mfma_f32_16x16x32_bf16 v[6:9], v[6:9], v[2:5], 0
	s_waitcnt lgkmcnt(2)
	v_mfma_f32_16x16x32_bf16 v[22:25], v[10:13], v[156:159], v[6:9]
	ds_read_b128 v[10:13], v147 offset:64
	s_nop 4
	ds_read_b128 v[6:9], v147
	s_waitcnt lgkmcnt(3)
	v_mfma_f32_16x16x32_bf16 v[14:17], v[14:17], v[2:5], 0
	s_waitcnt lgkmcnt(0)
	v_mfma_f32_16x16x32_bf16 v[6:9], v[6:9], v[2:5], 0
	v_mfma_f32_16x16x32_bf16 v[18:21], v[18:21], v[156:159], v[14:17]
	v_mfma_f32_16x16x32_bf16 v[14:17], v[10:13], v[156:159], v[6:9]
	s_nop 5
	ds_read_b128 v[6:9], v148
	ds_read_b128 v[10:13], v148 offset:64
	s_waitcnt lgkmcnt(1)
	v_mfma_f32_16x16x32_bf16 v[6:9], v[6:9], v[2:5], 0
	ds_read_b128 v[180:183], v150 offset:64
	s_waitcnt lgkmcnt(1)
	v_mfma_f32_16x16x32_bf16 v[10:13], v[10:13], v[156:159], v[6:9]
	s_nop 4
	ds_read_b128 v[6:9], v150
	s_waitcnt lgkmcnt(0)
	v_mfma_f32_16x16x32_bf16 v[6:9], v[6:9], v[2:5], 0
	v_mfma_f32_16x16x32_bf16 v[6:9], v[180:183], v[156:159], v[6:9]
	ds_read_b128 v[180:183], v152
	s_waitcnt lgkmcnt(0)
	v_mfma_f32_16x16x32_bf16 v[2:5], v[180:183], v[2:5], 0
	ds_read_b128 v[180:183], v152 offset:64
	s_waitcnt lgkmcnt(0)
; __global__ void __launch_bounds__(NTHREADS, 2) fwd_megakernel(Params p_arg) {
;     ...
;           const float slope = exp2f(-(float)(h + 1));
;           const float sinkv = pk->attn_sink[(size_t)l * 8 + h];
;           float d0 = (float)(kt0 * 16 + fq * 4 - 128 - qi);
;           asm volatile("" : "+v"(d0));
;           const float lo2 = fmaxf(-128.f, klo - 128.f - (float)qi), hi2 = fminf(128.f, khi - 129.f - (float)qi);
;           float mx = sinkv;
; #pragma unroll
;           for (int i = 0; i < 18; ++i)
; #pragma unroll
;             for (int r = 0; r < 4; ++r) {
;               float t = d0 + (float)(i * 16 + r);
;               bool ok = (t >= lo2) && (t <= hi2);
;               float v = ok ? (S[i][r] - slope * fabsf(t)) : -1e30f;
;               S[i][r] = v; mx = fmaxf(mx, v);
;             }
	v_mfma_f32_16x16x32_bf16 v[2:5], v[180:183], v[156:159], v[2:5]
	v_cvt_f32_u32_e32 v0, s0
	s_mov_b32 s1, 0x42fc0000
	v_mov_b32_e32 v155, v112
	v_cmp_lt_f32_e32 vcc, s1, v0
	s_and_b64 s[14:15], vcc, exec
	s_nop 0
	v_cndmask_b32_e32 v101, 0, v178, vcc
	v_sub_f32_e32 v0, v101, v0
	v_exp_f32_e32 v0, v0
	s_cselect_b32 s1, 0xffffffc0, 0
	v_ldexp_f32 v101, v0, s1
	global_load_dword v0, v1, s[12:13]
	s_nop 0
	v_cmp_ge_f32_e32 vcc, v155, v153
	v_cmp_le_f32_e64 s[14:15], v155, v154
	s_and_b64 vcc, vcc, s[14:15]
	v_fma_f32 v70, -v101, |v155|, v70
	v_add_f32_e32 v151, 1.0, v155
	v_cndmask_b32_e32 v70, v179, v70, vcc
	v_cmp_ge_f32_e32 vcc, v151, v153
	v_cmp_le_f32_e64 s[14:15], v151, v154
	s_and_b64 vcc, vcc, s[14:15]
	v_fma_f32 v71, -v101, |v151|, v71
	v_add_f32_e32 v156, 2.0, v155
	v_cndmask_b32_e32 v71, v179, v71, vcc
	v_cmp_ge_f32_e32 vcc, v156, v153
	v_cmp_le_f32_e64 s[14:15], v156, v154
	s_and_b64 vcc, vcc, s[14:15]
	v_fma_f32 v72, -v101, |v156|, v72
	v_add_f32_e32 v156, 0x40400000, v155
	v_cndmask_b32_e32 v72, v179, v72, vcc
	v_cmp_ge_f32_e32 vcc, v156, v153
	v_cmp_le_f32_e64 s[14:15], v156, v154
	s_and_b64 vcc, vcc, s[14:15]
	v_fma_f32 v73, -v101, |v156|, v73
	v_add_f32_e32 v156, 0x41800000, v155
	v_cndmask_b32_e32 v73, v179, v73, vcc
	v_cmp_ge_f32_e32 vcc, v156, v153
	v_cmp_le_f32_e64 s[14:15], v156, v154
	s_and_b64 vcc, vcc, s[14:15]
	v_fma_f32 v66, -v101, |v156|, v66
	v_add_f32_e32 v156, 0x41880000, v155
	v_cndmask_b32_e32 v66, v179, v66, vcc
	v_cmp_ge_f32_e32 vcc, v156, v153
	v_cmp_le_f32_e64 s[14:15], v156, v154
	s_and_b64 vcc, vcc, s[14:15]
	v_fma_f32 v67, -v101, |v156|, v67
	v_add_f32_e32 v156, 0x41900000, v155
	v_cndmask_b32_e32 v67, v179, v67, vcc
	v_cmp_ge_f32_e32 vcc, v156, v153
	v_cmp_le_f32_e64 s[14:15], v156, v154
	s_and_b64 vcc, vcc, s[14:15]
	v_fma_f32 v68, -v101, |v156|, v68
	v_add_f32_e32 v156, 0x41980000, v155
	v_cndmask_b32_e32 v68, v179, v68, vcc
	v_cmp_ge_f32_e32 vcc, v156, v153
	v_cmp_le_f32_e64 s[14:15], v156, v154
	s_and_b64 vcc, vcc, s[14:15]
	v_fma_f32 v69, -v101, |v156|, v69
	v_add_f32_e32 v156, 0x42000000, v155
	v_cndmask_b32_e32 v69, v179, v69, vcc
	v_cmp_ge_f32_e32 vcc, v156, v153
	v_cmp_le_f32_e64 s[14:15], v156, v154
	s_and_b64 vcc, vcc, s[14:15]
	v_fma_f32 v62, -v101, |v156|, v62
	v_add_f32_e32 v156, 0x42040000, v155
	v_cndmask_b32_e32 v62, v179, v62, vcc
	v_cmp_ge_f32_e32 vcc, v156, v153
	v_cmp_le_f32_e64 s[14:15], v156, v154
	s_and_b64 vcc, vcc, s[14:15]
	v_fma_f32 v63, -v101, |v156|, v63
	v_add_f32_e32 v156, 0x42080000, v155
	v_cndmask_b32_e32 v63, v179, v63, vcc
	v_cmp_ge_f32_e32 vcc, v156, v153
	v_cmp_le_f32_e64 s[14:15], v156, v154
	s_and_b64 vcc, vcc, s[14:15]
	v_fma_f32 v64, -v101, |v156|, v64
	v_add_f32_e32 v156, 0x420c0000, v155
	v_cndmask_b32_e32 v64, v179, v64, vcc
	v_cmp_ge_f32_e32 vcc, v156, v153
	v_cmp_le_f32_e64 s[14:15], v156, v154
	s_and_b64 vcc, vcc, s[14:15]
	v_fma_f32 v65, -v101, |v156|, v65
	v_add_f32_e32 v156, 0x42400000, v155
	v_cndmask_b32_e32 v65, v179, v65, vcc
	v_cmp_ge_f32_e32 vcc, v156, v153
	v_cmp_le_f32_e64 s[14:15], v156, v154
	s_and_b64 vcc, vcc, s[14:15]
	v_fma_f32 v58, -v101, |v156|, v58
	v_add_f32_e32 v156, 0x42440000, v155
	v_cndmask_b32_e32 v58, v179, v58, vcc
	v_cmp_ge_f32_e32 vcc, v156, v153
	v_cmp_le_f32_e64 s[14:15], v156, v154
	s_and_b64 vcc, vcc, s[14:15]
	v_fma_f32 v59, -v101, |v156|, v59
	v_add_f32_e32 v156, 0x42480000, v155
	v_cndmask_b32_e32 v59, v179, v59, vcc
	v_cmp_ge_f32_e32 vcc, v156, v153
	v_cmp_le_f32_e64 s[14:15], v156, v154
	s_and_b64 vcc, vcc, s[14:15]
	v_fma_f32 v60, -v101, |v156|, v60
	v_add_f32_e32 v156, 0x424c0000, v155
	v_cndmask_b32_e32 v60, v179, v60, vcc
	v_cmp_ge_f32_e32 vcc, v156, v153
	v_cmp_le_f32_e64 s[14:15], v156, v154
	s_and_b64 vcc, vcc, s[14:15]
	v_fma_f32 v61, -v101, |v156|, v61
	v_add_f32_e32 v156, 0x42800000, v155
	v_cndmask_b32_e32 v61, v179, v61, vcc
	v_cmp_ge_f32_e32 vcc, v156, v153
	v_cmp_le_f32_e64 s[14:15], v156, v154
	s_and_b64 vcc, vcc, s[14:15]
	v_fma_f32 v54, -v101, |v156|, v54
	v_add_f32_e32 v156, 0x42820000, v155
	v_cndmask_b32_e32 v54, v179, v54, vcc
	v_cmp_ge_f32_e32 vcc, v156, v153
	v_cmp_le_f32_e64 s[14:15], v156, v154
	s_and_b64 vcc, vcc, s[14:15]
	v_fma_f32 v55, -v101, |v156|, v55
	v_add_f32_e32 v156, 0x42840000, v155
	v_cndmask_b32_e32 v55, v179, v55, vcc
	v_cmp_ge_f32_e32 vcc, v156, v153
	v_cmp_le_f32_e64 s[14:15], v156, v154
	s_and_b64 vcc, vcc, s[14:15]
	v_fma_f32 v56, -v101, |v156|, v56
	v_add_f32_e32 v156, 0x42860000, v155
	v_cndmask_b32_e32 v56, v179, v56, vcc
	v_cmp_ge_f32_e32 vcc, v156, v153
	v_cmp_le_f32_e64 s[14:15], v156, v154
	s_and_b64 vcc, vcc, s[14:15]
	v_fma_f32 v57, -v101, |v156|, v57
	v_add_f32_e32 v156, 0x42a00000, v155
	v_cndmask_b32_e32 v57, v179, v57, vcc
	v_cmp_ge_f32_e32 vcc, v156, v153
	v_cmp_le_f32_e64 s[14:15], v156, v154
	s_and_b64 vcc, vcc, s[14:15]
	v_fma_f32 v50, -v101, |v156|, v50
	v_add_f32_e32 v156, 0x42a20000, v155
	v_cndmask_b32_e32 v50, v179, v50, vcc
	v_cmp_ge_f32_e32 vcc, v156, v153
	v_cmp_le_f32_e64 s[14:15], v156, v154
	s_and_b64 vcc, vcc, s[14:15]
	v_fma_f32 v51, -v101, |v156|, v51
	v_add_f32_e32 v156, 0x42a40000, v155
	v_cndmask_b32_e32 v51, v179, v51, vcc
	v_cmp_ge_f32_e32 vcc, v156, v153
	v_cmp_le_f32_e64 s[14:15], v156, v154
	s_and_b64 vcc, vcc, s[14:15]
	v_fma_f32 v52, -v101, |v156|, v52
	v_add_f32_e32 v156, 0x42a60000, v155
	v_cndmask_b32_e32 v52, v179, v52, vcc
	v_cmp_ge_f32_e32 vcc, v156, v153
	v_cmp_le_f32_e64 s[14:15], v156, v154
	s_and_b64 vcc, vcc, s[14:15]
	v_fma_f32 v53, -v101, |v156|, v53
	v_add_f32_e32 v156, 0x42c00000, v155
	v_cndmask_b32_e32 v53, v179, v53, vcc
	v_cmp_ge_f32_e32 vcc, v156, v153
	v_cmp_le_f32_e64 s[14:15], v156, v154
	s_and_b64 vcc, vcc, s[14:15]
	v_fma_f32 v46, -v101, |v156|, v46
	v_add_f32_e32 v156, 0x42c20000, v155
	v_cndmask_b32_e32 v46, v179, v46, vcc
	v_cmp_ge_f32_e32 vcc, v156, v153
	v_cmp_le_f32_e64 s[14:15], v156, v154
	s_and_b64 vcc, vcc, s[14:15]
	v_fma_f32 v47, -v101, |v156|, v47
	v_add_f32_e32 v156, 0x42c40000, v155
	v_cndmask_b32_e32 v47, v179, v47, vcc
	v_cmp_ge_f32_e32 vcc, v156, v153
	v_cmp_le_f32_e64 s[14:15], v156, v154
	s_waitcnt vmcnt(0)
; __global__ void __launch_bounds__(NTHREADS, 2) fwd_megakernel(Params p_arg) {
;     ...
;           float mx = sinkv;
; #pragma unroll
;           for (int i = 0; i < 18; ++i)
; #pragma unroll
;             for (int r = 0; r < 4; ++r) {
;               float t = d0 + (float)(i * 16 + r);
;               bool ok = (t >= lo2) && (t <= hi2);
;               float v = ok ? (S[i][r] - slope * fabsf(t)) : -1e30f;
;               S[i][r] = v; mx = fmaxf(mx, v);
;             }
	v_max3_f32 v151, v0, v70, v71
	s_and_b64 vcc, vcc, s[14:15]
	v_fma_f32 v48, -v101, |v156|, v48
	v_add_f32_e32 v156, 0x42c60000, v155
	v_max3_f32 v151, v151, v72, v73
	v_cndmask_b32_e32 v48, v179, v48, vcc
	v_cmp_ge_f32_e32 vcc, v156, v153
	v_cmp_le_f32_e64 s[14:15], v156, v154
	v_max3_f32 v151, v151, v66, v67
	s_and_b64 vcc, vcc, s[14:15]
	v_fma_f32 v49, -v101, |v156|, v49
	v_add_f32_e32 v156, 0x42e00000, v155
	v_max3_f32 v151, v151, v68, v69
	v_cndmask_b32_e32 v49, v179, v49, vcc
	v_cmp_ge_f32_e32 vcc, v156, v153
	v_cmp_le_f32_e64 s[14:15], v156, v154
	v_max3_f32 v151, v151, v62, v63
	s_and_b64 vcc, vcc, s[14:15]
	v_fma_f32 v42, -v101, |v156|, v42
	v_add_f32_e32 v156, 0x42e20000, v155
	v_max3_f32 v151, v151, v64, v65
	v_cndmask_b32_e32 v42, v179, v42, vcc
	v_cmp_ge_f32_e32 vcc, v156, v153
	v_cmp_le_f32_e64 s[14:15], v156, v154
	v_max3_f32 v151, v151, v58, v59
	s_and_b64 vcc, vcc, s[14:15]
	v_fma_f32 v43, -v101, |v156|, v43
	v_add_f32_e32 v156, 0x42e40000, v155
	v_max3_f32 v151, v151, v60, v61
	v_cndmask_b32_e32 v43, v179, v43, vcc
	v_cmp_ge_f32_e32 vcc, v156, v153
	v_cmp_le_f32_e64 s[14:15], v156, v154
	v_max3_f32 v151, v151, v54, v55
	s_and_b64 vcc, vcc, s[14:15]
	v_fma_f32 v44, -v101, |v156|, v44
	v_add_f32_e32 v156, 0x42e60000, v155
	v_max3_f32 v151, v151, v56, v57
	v_cndmask_b32_e32 v44, v179, v44, vcc
	v_cmp_ge_f32_e32 vcc, v156, v153
	v_cmp_le_f32_e64 s[14:15], v156, v154
	v_max3_f32 v151, v151, v50, v51
	s_and_b64 vcc, vcc, s[14:15]
	v_fma_f32 v45, -v101, |v156|, v45
	v_add_f32_e32 v156, 0x43000000, v155
	v_max3_f32 v151, v151, v52, v53
	v_cndmask_b32_e32 v45, v179, v45, vcc
	v_cmp_ge_f32_e32 vcc, v156, v153
	v_cmp_le_f32_e64 s[14:15], v156, v154
	v_max3_f32 v151, v151, v46, v47
	s_and_b64 vcc, vcc, s[14:15]
	v_fma_f32 v38, -v101, |v156|, v38
	v_add_f32_e32 v156, 0x43010000, v155
	v_max3_f32 v151, v151, v48, v49
	v_cndmask_b32_e32 v38, v179, v38, vcc
	v_cmp_ge_f32_e32 vcc, v156, v153
	v_cmp_le_f32_e64 s[14:15], v156, v154
	v_max3_f32 v151, v151, v42, v43
	s_and_b64 vcc, vcc, s[14:15]
	v_fma_f32 v39, -v101, |v156|, v39
	v_max3_f32 v151, v151, v44, v45
	v_cndmask_b32_e32 v156, v179, v39, vcc
	v_max3_f32 v39, v151, v38, v156
	v_add_f32_e32 v151, 0x43020000, v155
	v_cmp_ge_f32_e32 vcc, v151, v153
	v_cmp_le_f32_e64 s[14:15], v151, v154
	s_and_b64 vcc, vcc, s[14:15]
	v_fma_f32 v40, -v101, |v151|, v40
	v_add_f32_e32 v151, 0x43030000, v155
	v_cndmask_b32_e32 v40, v179, v40, vcc
	v_cmp_ge_f32_e32 vcc, v151, v153
	v_cmp_le_f32_e64 s[14:15], v151, v154
	s_and_b64 vcc, vcc, s[14:15]
	v_fma_f32 v41, -v101, |v151|, v41
	v_cndmask_b32_e32 v157, v179, v41, vcc
	v_add_f32_e32 v41, 0x43100000, v155
	v_cmp_ge_f32_e32 vcc, v41, v153
	v_cmp_le_f32_e64 s[14:15], v41, v154
	s_and_b64 vcc, vcc, s[14:15]
	v_fma_f32 v34, -v101, |v41|, v34
	v_add_f32_e32 v41, 0x43110000, v155
	v_cndmask_b32_e32 v34, v179, v34, vcc
	v_cmp_ge_f32_e32 vcc, v41, v153
	v_cmp_le_f32_e64 s[14:15], v41, v154
	s_and_b64 vcc, vcc, s[14:15]
	v_fma_f32 v35, -v101, |v41|, v35
	v_max3_f32 v39, v39, v40, v157
	v_cndmask_b32_e32 v158, v179, v35, vcc
	v_max3_f32 v35, v39, v34, v158
	v_add_f32_e32 v39, 0x43120000, v155
	v_cmp_ge_f32_e32 vcc, v39, v153
	v_cmp_le_f32_e64 s[14:15], v39, v154
	s_and_b64 vcc, vcc, s[14:15]
	v_fma_f32 v36, -v101, |v39|, v36
	v_add_f32_e32 v39, 0x43130000, v155
	v_cndmask_b32_e32 v36, v179, v36, vcc
	v_cmp_ge_f32_e32 vcc, v39, v153
	v_cmp_le_f32_e64 s[14:15], v39, v154
	s_and_b64 vcc, vcc, s[14:15]
	v_fma_f32 v37, -v101, |v39|, v37
	v_cndmask_b32_e32 v159, v179, v37, vcc
	v_add_f32_e32 v37, 0x43200000, v155
	v_cmp_ge_f32_e32 vcc, v37, v153
	v_cmp_le_f32_e64 s[14:15], v37, v154
	s_and_b64 vcc, vcc, s[14:15]
	v_fma_f32 v30, -v101, |v37|, v30
	v_add_f32_e32 v37, 0x43210000, v155
	v_cndmask_b32_e32 v30, v179, v30, vcc
	v_cmp_ge_f32_e32 vcc, v37, v153
	v_cmp_le_f32_e64 s[14:15], v37, v154
	s_and_b64 vcc, vcc, s[14:15]
	v_fma_f32 v31, -v101, |v37|, v31
	v_max3_f32 v35, v35, v36, v159
	v_cndmask_b32_e32 v160, v179, v31, vcc
	v_max3_f32 v31, v35, v30, v160
	v_add_f32_e32 v35, 0x43220000, v155
	v_cmp_ge_f32_e32 vcc, v35, v153
	v_cmp_le_f32_e64 s[14:15], v35, v154
	s_and_b64 vcc, vcc, s[14:15]
	v_fma_f32 v32, -v101, |v35|, v32
	v_add_f32_e32 v35, 0x43230000, v155
	v_cndmask_b32_e32 v32, v179, v32, vcc
	v_cmp_ge_f32_e32 vcc, v35, v153
	v_cmp_le_f32_e64 s[14:15], v35, v154
	s_and_b64 vcc, vcc, s[14:15]
	v_fma_f32 v33, -v101, |v35|, v33
	v_cndmask_b32_e32 v161, v179, v33, vcc
	v_add_f32_e32 v33, 0x43300000, v155
	v_cmp_ge_f32_e32 vcc, v33, v153
	v_cmp_le_f32_e64 s[14:15], v33, v154
	s_and_b64 vcc, vcc, s[14:15]
	v_fma_f32 v26, -v101, |v33|, v26
	v_add_f32_e32 v33, 0x43310000, v155
	v_cndmask_b32_e32 v26, v179, v26, vcc
	v_cmp_ge_f32_e32 vcc, v33, v153
	v_cmp_le_f32_e64 s[14:15], v33, v154
	s_and_b64 vcc, vcc, s[14:15]
	v_fma_f32 v27, -v101, |v33|, v27
	v_max3_f32 v31, v31, v32, v161
	v_cndmask_b32_e32 v180, v179, v27, vcc
	v_max3_f32 v27, v31, v26, v180
	v_add_f32_e32 v31, 0x43320000, v155
	v_cmp_ge_f32_e32 vcc, v31, v153
	v_cmp_le_f32_e64 s[14:15], v31, v154
	s_and_b64 vcc, vcc, s[14:15]
	v_fma_f32 v28, -v101, |v31|, v28
	v_add_f32_e32 v31, 0x43330000, v155
	v_cndmask_b32_e32 v28, v179, v28, vcc
	v_cmp_ge_f32_e32 vcc, v31, v153
	v_cmp_le_f32_e64 s[14:15], v31, v154
	s_and_b64 vcc, vcc, s[14:15]
	v_fma_f32 v29, -v101, |v31|, v29
	v_cndmask_b32_e32 v181, v179, v29, vcc
	v_add_f32_e32 v29, 0x43400000, v155
	v_cmp_ge_f32_e32 vcc, v29, v153
	v_cmp_le_f32_e64 s[14:15], v29, v154
	s_and_b64 vcc, vcc, s[14:15]
	v_fma_f32 v22, -v101, |v29|, v22
	v_add_f32_e32 v29, 0x43410000, v155
	v_cndmask_b32_e32 v22, v179, v22, vcc
	v_cmp_ge_f32_e32 vcc, v29, v153
	v_cmp_le_f32_e64 s[14:15], v29, v154
; __global__ void __launch_bounds__(NTHREADS, 2) fwd_megakernel(Params p_arg) {
;     ...
;           float mx = sinkv;
; #pragma unroll
;           for (int i = 0; i < 18; ++i)
; #pragma unroll
;             for (int r = 0; r < 4; ++r) {
;               float t = d0 + (float)(i * 16 + r);
;               bool ok = (t >= lo2) && (t <= hi2);
;               float v = ok ? (S[i][r] - slope * fabsf(t)) : -1e30f;
;               S[i][r] = v; mx = fmaxf(mx, v);
;             }
;           mx = fmaxf(mx, __shfl_xor(mx, 16)); mx = fmaxf(mx, __shfl_xor(mx, 32));
	s_and_b64 vcc, vcc, s[14:15]
	v_fma_f32 v23, -v101, |v29|, v23
	v_max3_f32 v27, v27, v28, v181
	v_cndmask_b32_e32 v182, v179, v23, vcc
	v_max3_f32 v23, v27, v22, v182
	v_add_f32_e32 v27, 0x43420000, v155
	v_cmp_ge_f32_e32 vcc, v27, v153
	v_cmp_le_f32_e64 s[14:15], v27, v154
	s_and_b64 vcc, vcc, s[14:15]
	v_fma_f32 v24, -v101, |v27|, v24
	v_add_f32_e32 v27, 0x43430000, v155
	v_cndmask_b32_e32 v24, v179, v24, vcc
	v_cmp_ge_f32_e32 vcc, v27, v153
	v_cmp_le_f32_e64 s[14:15], v27, v154
	s_and_b64 vcc, vcc, s[14:15]
	v_fma_f32 v25, -v101, |v27|, v25
	v_cndmask_b32_e32 v183, v179, v25, vcc
	v_add_f32_e32 v25, 0x43500000, v155
	v_cmp_ge_f32_e32 vcc, v25, v153
	v_cmp_le_f32_e64 s[14:15], v25, v154
	s_and_b64 vcc, vcc, s[14:15]
	v_fma_f32 v18, -v101, |v25|, v18
	v_add_f32_e32 v25, 0x43510000, v155
	v_cndmask_b32_e32 v18, v179, v18, vcc
	v_cmp_ge_f32_e32 vcc, v25, v153
	v_cmp_le_f32_e64 s[14:15], v25, v154
	s_and_b64 vcc, vcc, s[14:15]
	v_fma_f32 v19, -v101, |v25|, v19
	v_max3_f32 v23, v23, v24, v183
	v_cndmask_b32_e32 v184, v179, v19, vcc
	v_max3_f32 v19, v23, v18, v184
	v_add_f32_e32 v23, 0x43520000, v155
	v_cmp_ge_f32_e32 vcc, v23, v153
	v_cmp_le_f32_e64 s[14:15], v23, v154
	s_and_b64 vcc, vcc, s[14:15]
	v_fma_f32 v20, -v101, |v23|, v20
	v_add_f32_e32 v23, 0x43530000, v155
	v_cndmask_b32_e32 v20, v179, v20, vcc
	v_cmp_ge_f32_e32 vcc, v23, v153
	v_cmp_le_f32_e64 s[14:15], v23, v154
	s_and_b64 vcc, vcc, s[14:15]
	v_fma_f32 v21, -v101, |v23|, v21
	v_cndmask_b32_e32 v186, v179, v21, vcc
	v_add_f32_e32 v21, 0x43600000, v155
	v_cmp_ge_f32_e32 vcc, v21, v153
	v_cmp_le_f32_e64 s[14:15], v21, v154
	s_and_b64 vcc, vcc, s[14:15]
	v_fma_f32 v14, -v101, |v21|, v14
	v_cndmask_b32_e32 v185, v179, v14, vcc
	v_add_f32_e32 v14, 0x43610000, v155
	v_cmp_ge_f32_e32 vcc, v14, v153
	v_cmp_le_f32_e64 s[14:15], v14, v154
	s_and_b64 vcc, vcc, s[14:15]
	v_fma_f32 v14, -v101, |v14|, v15
	v_max3_f32 v19, v19, v20, v186
	v_cndmask_b32_e32 v15, v179, v14, vcc
	v_max3_f32 v14, v19, v185, v15
	v_add_f32_e32 v19, 0x43620000, v155
	v_cmp_ge_f32_e32 vcc, v19, v153
	v_cmp_le_f32_e64 s[14:15], v19, v154
	s_and_b64 vcc, vcc, s[14:15]
	v_fma_f32 v16, -v101, |v19|, v16
	v_cndmask_b32_e32 v187, v179, v16, vcc
	v_add_f32_e32 v16, 0x43630000, v155
	v_cmp_ge_f32_e32 vcc, v16, v153
	v_cmp_le_f32_e64 s[14:15], v16, v154
	s_and_b64 vcc, vcc, s[14:15]
	v_fma_f32 v16, -v101, |v16|, v17
	v_cndmask_b32_e32 v189, v179, v16, vcc
	v_add_f32_e32 v16, 0x43700000, v155
	v_cmp_ge_f32_e32 vcc, v16, v153
	v_cmp_le_f32_e64 s[14:15], v16, v154
	s_and_b64 vcc, vcc, s[14:15]
	v_fma_f32 v10, -v101, |v16|, v10
	v_cndmask_b32_e32 v188, v179, v10, vcc
	v_add_f32_e32 v10, 0x43710000, v155
	v_cmp_ge_f32_e32 vcc, v10, v153
	v_cmp_le_f32_e64 s[14:15], v10, v154
	s_and_b64 vcc, vcc, s[14:15]
	v_fma_f32 v10, -v101, |v10|, v11
	v_add_f32_e32 v11, 0x43720000, v155
	v_cndmask_b32_e32 v190, v179, v10, vcc
	v_cmp_ge_f32_e32 vcc, v11, v153
	v_cmp_le_f32_e64 s[14:15], v11, v154
	s_and_b64 vcc, vcc, s[14:15]
	v_fma_f32 v11, -v101, |v11|, v12
	v_cndmask_b32_e32 v12, v179, v11, vcc
	v_add_f32_e32 v11, 0x43730000, v155
	v_cmp_ge_f32_e32 vcc, v11, v153
	v_cmp_le_f32_e64 s[14:15], v11, v154
	s_and_b64 vcc, vcc, s[14:15]
	v_fma_f32 v11, -v101, |v11|, v13
	v_cndmask_b32_e32 v192, v179, v11, vcc
	v_add_f32_e32 v11, 0x43800000, v155
	v_cmp_ge_f32_e32 vcc, v11, v153
	v_cmp_le_f32_e64 s[14:15], v11, v154
	s_and_b64 vcc, vcc, s[14:15]
	v_fma_f32 v6, -v101, |v11|, v6
	v_cndmask_b32_e32 v191, v179, v6, vcc
	v_add_f32_e32 v6, 0x43808000, v155
	v_max3_f32 v14, v14, v187, v189
	v_cmp_ge_f32_e32 vcc, v6, v153
	v_cmp_le_f32_e64 s[14:15], v6, v154
	v_max3_f32 v10, v14, v188, v190
	s_and_b64 vcc, vcc, s[14:15]
	v_fma_f32 v6, -v101, |v6|, v7
	v_max3_f32 v10, v10, v12, v192
	v_cndmask_b32_e32 v7, v179, v6, vcc
	v_max3_f32 v6, v10, v191, v7
	v_add_f32_e32 v10, 0x43810000, v155
	v_cmp_ge_f32_e32 vcc, v10, v153
	v_cmp_le_f32_e64 s[14:15], v10, v154
	s_and_b64 vcc, vcc, s[14:15]
	v_fma_f32 v8, -v101, |v10|, v8
	v_cndmask_b32_e32 v193, v179, v8, vcc
	v_add_f32_e32 v8, 0x43818000, v155
	v_cmp_ge_f32_e32 vcc, v8, v153
	v_cmp_le_f32_e64 s[14:15], v8, v154
	s_and_b64 vcc, vcc, s[14:15]
	v_fma_f32 v8, -v101, |v8|, v9
	v_cndmask_b32_e32 v195, v179, v8, vcc
	v_add_f32_e32 v8, 0x43880000, v155
	v_cmp_ge_f32_e32 vcc, v8, v153
	v_cmp_le_f32_e64 s[14:15], v8, v154
	s_and_b64 vcc, vcc, s[14:15]
	v_fma_f32 v2, -v101, |v8|, v2
	v_cndmask_b32_e32 v194, v179, v2, vcc
	v_add_f32_e32 v2, 0x43888000, v155
	v_cmp_ge_f32_e32 vcc, v2, v153
	v_cmp_le_f32_e64 s[14:15], v2, v154
	s_and_b64 vcc, vcc, s[14:15]
	v_fma_f32 v2, -v101, |v2|, v3
	v_add_f32_e32 v3, 0x43890000, v155
	v_cndmask_b32_e32 v196, v179, v2, vcc
	v_cmp_ge_f32_e32 vcc, v3, v153
	v_cmp_le_f32_e64 s[14:15], v3, v154
	s_and_b64 vcc, vcc, s[14:15]
	v_fma_f32 v3, -v101, |v3|, v4
	v_cndmask_b32_e32 v198, v179, v3, vcc
	v_add_f32_e32 v3, 0x43898000, v155
	v_cmp_ge_f32_e32 vcc, v3, v153
	v_cmp_le_f32_e64 s[14:15], v3, v154
	s_and_b64 vcc, vcc, s[14:15]
	v_fma_f32 v3, -v101, |v3|, v5
	v_max3_f32 v6, v6, v193, v195
	v_cndmask_b32_e32 v199, v179, v3, vcc
	v_cmp_lt_i32_e32 vcc, v169, v164
	v_max3_f32 v2, v6, v194, v196
	v_max3_f32 v2, v2, v198, v199
	v_cndmask_b32_e32 v3, v163, v169, vcc
	v_lshlrev_b32_e32 v101, 2, v3
	ds_bpermute_b32 v3, v101, v2
	v_cmp_lt_i32_e32 vcc, v170, v164
	s_waitcnt lgkmcnt(0)
	v_max_f32_e32 v3, v3, v3
	v_max_f32_e32 v2, v2, v3
	v_cndmask_b32_e32 v3, v163, v170, vcc
	v_lshlrev_b32_e32 v155, 2, v3
	ds_bpermute_b32 v3, v155, v2
	s_waitcnt lgkmcnt(0)
; __global__ void __launch_bounds__(NTHREADS, 2) fwd_megakernel(Params p_arg) {
;     ...
;           mx = fmaxf(mx, __shfl_xor(mx, 16)); mx = fmaxf(mx, __shfl_xor(mx, 32));
;           float sum = 0.f;
; #pragma unroll
;           for (int i = 0; i < 18; ++i)
; #pragma unroll
;             for (int r = 0; r < 4; ++r) { float pv = __expf(S[i][r] - mx); S[i][r] = pv; sum += pv; }
	v_max_f32_e32 v3, v3, v3
	v_max_f32_e32 v197, v2, v3
	v_sub_f32_e32 v3, v71, v197
	v_mul_f32_e32 v3, 0x3fb8aa3b, v3
	v_exp_f32_e32 v71, v3
	v_sub_f32_e32 v3, v72, v197
	v_mul_f32_e32 v3, 0x3fb8aa3b, v3
	v_exp_f32_e32 v72, v3
	v_sub_f32_e32 v3, v73, v197
	v_mul_f32_e32 v3, 0x3fb8aa3b, v3
	v_exp_f32_e32 v73, v3
	v_sub_f32_e32 v3, v66, v197
	v_mul_f32_e32 v3, 0x3fb8aa3b, v3
	v_exp_f32_e32 v66, v3
	v_sub_f32_e32 v3, v67, v197
	v_mul_f32_e32 v3, 0x3fb8aa3b, v3
	v_exp_f32_e32 v67, v3
	v_sub_f32_e32 v3, v68, v197
	v_mul_f32_e32 v3, 0x3fb8aa3b, v3
	v_exp_f32_e32 v68, v3
	v_sub_f32_e32 v3, v69, v197
	v_mul_f32_e32 v3, 0x3fb8aa3b, v3
	v_exp_f32_e32 v69, v3
	v_sub_f32_e32 v3, v62, v197
	v_mul_f32_e32 v3, 0x3fb8aa3b, v3
	v_exp_f32_e32 v62, v3
	v_sub_f32_e32 v3, v63, v197
	v_mul_f32_e32 v3, 0x3fb8aa3b, v3
	v_exp_f32_e32 v63, v3
	v_sub_f32_e32 v3, v64, v197
	v_mul_f32_e32 v3, 0x3fb8aa3b, v3
	v_exp_f32_e32 v64, v3
	v_sub_f32_e32 v3, v65, v197
	v_mul_f32_e32 v3, 0x3fb8aa3b, v3
	v_exp_f32_e32 v65, v3
	v_sub_f32_e32 v3, v58, v197
	v_mul_f32_e32 v3, 0x3fb8aa3b, v3
	v_exp_f32_e32 v58, v3
	v_sub_f32_e32 v3, v59, v197
	v_mul_f32_e32 v3, 0x3fb8aa3b, v3
	v_exp_f32_e32 v59, v3
	v_sub_f32_e32 v3, v60, v197
	v_mul_f32_e32 v3, 0x3fb8aa3b, v3
	v_exp_f32_e32 v60, v3
	v_sub_f32_e32 v3, v61, v197
	v_mul_f32_e32 v3, 0x3fb8aa3b, v3
	v_exp_f32_e32 v61, v3
	v_sub_f32_e32 v3, v54, v197
	v_mul_f32_e32 v3, 0x3fb8aa3b, v3
	v_exp_f32_e32 v35, v3
	v_sub_f32_e32 v3, v55, v197
	v_mul_f32_e32 v3, 0x3fb8aa3b, v3
	v_exp_f32_e32 v39, v3
	v_sub_f32_e32 v3, v56, v197
	v_mul_f32_e32 v3, 0x3fb8aa3b, v3
	v_exp_f32_e32 v54, v3
	v_sub_f32_e32 v3, v57, v197
	v_mul_f32_e32 v3, 0x3fb8aa3b, v3
	v_exp_f32_e32 v55, v3
	v_sub_f32_e32 v3, v50, v197
	v_mul_f32_e32 v3, 0x3fb8aa3b, v3
	v_exp_f32_e32 v50, v3
	v_sub_f32_e32 v3, v51, v197
	v_mul_f32_e32 v3, 0x3fb8aa3b, v3
	v_exp_f32_e32 v56, v3
	v_sub_f32_e32 v3, v52, v197
	v_mul_f32_e32 v3, 0x3fb8aa3b, v3
	v_exp_f32_e32 v57, v3
	v_sub_f32_e32 v3, v53, v197
	v_mul_f32_e32 v3, 0x3fb8aa3b, v3
	v_exp_f32_e32 v53, v3
	v_sub_f32_e32 v3, v46, v197
	v_mul_f32_e32 v3, 0x3fb8aa3b, v3
	v_exp_f32_e32 v27, v3
	v_sub_f32_e32 v3, v47, v197
	v_mul_f32_e32 v3, 0x3fb8aa3b, v3
	v_exp_f32_e32 v31, v3
	v_sub_f32_e32 v3, v48, v197
	v_mul_f32_e32 v3, 0x3fb8aa3b, v3
	v_exp_f32_e32 v37, v3
	v_sub_f32_e32 v3, v49, v197
	v_mul_f32_e32 v3, 0x3fb8aa3b, v3
	v_exp_f32_e32 v41, v3
	v_sub_f32_e32 v3, v42, v197
	v_mul_f32_e32 v3, 0x3fb8aa3b, v3
	v_exp_f32_e32 v46, v3
	v_sub_f32_e32 v3, v43, v197
	v_mul_f32_e32 v3, 0x3fb8aa3b, v3
	v_exp_f32_e32 v48, v3
	v_sub_f32_e32 v3, v44, v197
	v_mul_f32_e32 v3, 0x3fb8aa3b, v3
	v_exp_f32_e32 v51, v3
	v_sub_f32_e32 v3, v45, v197
	v_sub_f32_e32 v2, v70, v197
	v_mul_f32_e32 v3, 0x3fb8aa3b, v3
	v_mul_f32_e32 v2, 0x3fb8aa3b, v2
	v_exp_f32_e32 v52, v3
	v_sub_f32_e32 v3, v38, v197
	v_exp_f32_e32 v70, v2
	v_mul_f32_e32 v3, 0x3fb8aa3b, v3
	v_exp_f32_e32 v19, v3
	v_sub_f32_e32 v3, v156, v197
	v_mul_f32_e32 v3, 0x3fb8aa3b, v3
	v_exp_f32_e32 v23, v3
	v_sub_f32_e32 v3, v40, v197
	v_add_f32_e32 v2, 0, v70
	v_mul_f32_e32 v3, 0x3fb8aa3b, v3
	v_add_f32_e32 v2, v2, v71
	v_exp_f32_e32 v29, v3
	v_sub_f32_e32 v3, v157, v197
	v_add_f32_e32 v2, v2, v72
	v_mul_f32_e32 v3, 0x3fb8aa3b, v3
	v_add_f32_e32 v2, v2, v73
	v_exp_f32_e32 v33, v3
	v_sub_f32_e32 v3, v34, v197
	v_add_f32_e32 v2, v2, v66
	v_mul_f32_e32 v3, 0x3fb8aa3b, v3
	v_add_f32_e32 v2, v2, v67
	v_exp_f32_e32 v42, v3
	v_sub_f32_e32 v3, v158, v197
	v_add_f32_e32 v2, v2, v68
	v_mul_f32_e32 v3, 0x3fb8aa3b, v3
	v_add_f32_e32 v2, v2, v69
	v_exp_f32_e32 v44, v3
	v_sub_f32_e32 v3, v36, v197
	v_add_f32_e32 v2, v2, v62
	v_mul_f32_e32 v3, 0x3fb8aa3b, v3
	v_add_f32_e32 v2, v2, v63
	v_exp_f32_e32 v47, v3
	v_sub_f32_e32 v3, v159, v197
	v_add_f32_e32 v2, v2, v64
	v_mul_f32_e32 v3, 0x3fb8aa3b, v3
	v_add_f32_e32 v2, v2, v65
	v_exp_f32_e32 v49, v3
	v_sub_f32_e32 v3, v30, v197
	v_add_f32_e32 v2, v2, v58
	v_mul_f32_e32 v3, 0x3fb8aa3b, v3
	v_add_f32_e32 v2, v2, v59
	v_exp_f32_e32 v13, v3
	v_sub_f32_e32 v3, v160, v197
	v_add_f32_e32 v2, v2, v60
	v_mul_f32_e32 v3, 0x3fb8aa3b, v3
	v_add_f32_e32 v2, v2, v61
	v_exp_f32_e32 v16, v3
	v_sub_f32_e32 v3, v32, v197
	v_add_f32_e32 v2, v2, v35
	v_mul_f32_e32 v3, 0x3fb8aa3b, v3
	v_add_f32_e32 v2, v2, v39
	v_exp_f32_e32 v21, v3
	v_sub_f32_e32 v3, v161, v197
	v_add_f32_e32 v2, v2, v54
	v_mul_f32_e32 v3, 0x3fb8aa3b, v3
	v_add_f32_e32 v2, v2, v55
	v_exp_f32_e32 v25, v3
	v_sub_f32_e32 v3, v26, v197
	v_add_f32_e32 v2, v2, v50
	v_mul_f32_e32 v3, 0x3fb8aa3b, v3
	v_add_f32_e32 v2, v2, v56
	v_exp_f32_e32 v34, v3
	v_sub_f32_e32 v3, v180, v197
	v_add_f32_e32 v2, v2, v57
	v_mul_f32_e32 v3, 0x3fb8aa3b, v3
	v_add_f32_e32 v2, v2, v53
	v_exp_f32_e32 v38, v3
	v_sub_f32_e32 v3, v28, v197
	v_add_f32_e32 v2, v2, v27
	v_mul_f32_e32 v3, 0x3fb8aa3b, v3
	v_add_f32_e32 v2, v2, v31
	v_exp_f32_e32 v43, v3
	v_sub_f32_e32 v3, v181, v197
	v_add_f32_e32 v2, v2, v37
	v_mul_f32_e32 v3, 0x3fb8aa3b, v3
	v_add_f32_e32 v2, v2, v41
	v_exp_f32_e32 v45, v3
	v_sub_f32_e32 v3, v22, v197
	v_add_f32_e32 v2, v2, v46
	v_mul_f32_e32 v3, 0x3fb8aa3b, v3
	v_add_f32_e32 v2, v2, v48
	v_exp_f32_e32 v8, v3
	v_sub_f32_e32 v3, v182, v197
	v_add_f32_e32 v2, v2, v51
	v_mul_f32_e32 v3, 0x3fb8aa3b, v3
	v_add_f32_e32 v2, v2, v52
	v_exp_f32_e32 v10, v3
	v_sub_f32_e32 v3, v24, v197
	v_add_f32_e32 v2, v2, v19
	v_mul_f32_e32 v3, 0x3fb8aa3b, v3
	v_add_f32_e32 v2, v2, v23
	v_exp_f32_e32 v14, v3
	v_sub_f32_e32 v3, v183, v197
	v_add_f32_e32 v2, v2, v29
	v_mul_f32_e32 v3, 0x3fb8aa3b, v3
	v_add_f32_e32 v2, v2, v33
	v_exp_f32_e32 v17, v3
	v_sub_f32_e32 v3, v18, v197
	v_add_f32_e32 v2, v2, v42
	v_mul_f32_e32 v3, 0x3fb8aa3b, v3
	v_add_f32_e32 v2, v2, v44
	v_exp_f32_e32 v26, v3
; __device__ __forceinline__ float rcpf(float x) { return __builtin_amdgcn_rcpf(x); }
; __global__ void __launch_bounds__(NTHREADS, 2) fwd_megakernel(Params p_arg) {
;     ...
;           for (int i = 0; i < 18; ++i)
; #pragma unroll
;             for (int r = 0; r < 4; ++r) { float pv = __expf(S[i][r] - mx); S[i][r] = pv; sum += pv; }
;           sum += __shfl_xor(sum, 16); sum += __shfl_xor(sum, 32);
;           const float inv = rcpf(sum + __expf(sinkv - mx));
;           f32x4 O[4];
; #pragma unroll
;           for (int dt = 0; dt < 4; ++dt) O[dt] = f32x4{0.f, 0.f, 0.f, 0.f};
; #pragma unroll
;           for (int pp = 0; pp < 9; ++pp) {
;             union { bf16x8 v; uint32_t u[4]; } pf;
;             pf.u[0] = pack2(S[2*pp][0], S[2*pp][1]); pf.u[1] = pack2(S[2*pp][2], S[2*pp][3]);
;             pf.u[2] = pack2(S[2*pp+1][0], S[2*pp+1][1]); pf.u[3] = pack2(S[2*pp+1][2], S[2*pp+1][3]);
; #pragma unroll
;             for (int dt = 0; dt < 4; ++dt) {
;               union { bf16x8 v; uint2 h2[2]; } vfr;
;               const u16* vb = VT + (dt * 16 + fr) * 392 + (kt0 + 2 * pp) * 16 + fq * 4;
;               vfr.h2[0] = *(const uint2*)(vb);
;               vfr.h2[1] = *(const uint2*)(vb + 16);
;               O[dt] = __builtin_amdgcn_mfma_f32_16x16x32_bf16(vfr.v, pf.v, O[dt], 0, 0, 0);
;             }
;             __builtin_amdgcn_sched_barrier(0);
;           }
	v_sub_f32_e32 v3, v184, v197
	v_add_f32_e32 v2, v2, v47
	v_mul_f32_e32 v3, 0x3fb8aa3b, v3
	v_add_f32_e32 v2, v2, v49
	v_exp_f32_e32 v30, v3
	v_sub_f32_e32 v3, v20, v197
	v_add_f32_e32 v2, v2, v13
	v_mul_f32_e32 v3, 0x3fb8aa3b, v3
	v_add_f32_e32 v2, v2, v16
	v_exp_f32_e32 v36, v3
	v_sub_f32_e32 v3, v186, v197
	v_add_f32_e32 v2, v2, v21
	v_mul_f32_e32 v3, 0x3fb8aa3b, v3
	v_add_f32_e32 v2, v2, v25
	v_exp_f32_e32 v40, v3
	v_sub_f32_e32 v3, v185, v197
	v_add_f32_e32 v2, v2, v34
	v_mul_f32_e32 v3, 0x3fb8aa3b, v3
	v_add_f32_e32 v2, v2, v38
	v_exp_f32_e32 v4, v3
	v_sub_f32_e32 v3, v15, v197
	v_add_f32_e32 v2, v2, v43
	v_mul_f32_e32 v3, 0x3fb8aa3b, v3
	v_add_f32_e32 v2, v2, v45
	v_exp_f32_e32 v6, v3
	v_sub_f32_e32 v3, v187, v197
	v_add_f32_e32 v2, v2, v8
	v_mul_f32_e32 v3, 0x3fb8aa3b, v3
	v_add_f32_e32 v2, v2, v10
	v_exp_f32_e32 v9, v3
	v_sub_f32_e32 v3, v189, v197
	v_add_f32_e32 v2, v2, v14
	v_mul_f32_e32 v3, 0x3fb8aa3b, v3
	v_add_f32_e32 v2, v2, v17
	v_exp_f32_e32 v11, v3
	v_sub_f32_e32 v3, v188, v197
	v_add_f32_e32 v2, v2, v26
	v_mul_f32_e32 v3, 0x3fb8aa3b, v3
	v_add_f32_e32 v2, v2, v30
	v_exp_f32_e32 v18, v3
	v_sub_f32_e32 v3, v190, v197
	v_add_f32_e32 v2, v2, v36
	v_mul_f32_e32 v3, 0x3fb8aa3b, v3
	v_add_f32_e32 v2, v2, v40
	v_exp_f32_e32 v22, v3
	v_sub_f32_e32 v3, v12, v197
	v_add_f32_e32 v2, v2, v4
	v_mul_f32_e32 v3, 0x3fb8aa3b, v3
	v_add_f32_e32 v2, v2, v6
	v_exp_f32_e32 v28, v3
	v_sub_f32_e32 v3, v192, v197
	v_add_f32_e32 v2, v2, v9
	v_mul_f32_e32 v3, 0x3fb8aa3b, v3
	v_add_f32_e32 v2, v2, v11
	v_exp_f32_e32 v32, v3
	v_add_f32_e32 v2, v2, v18
	v_add_f32_e32 v2, v2, v22
	v_add_f32_e32 v2, v2, v28
	v_add_f32_e32 v3, v2, v32
	v_sub_f32_e32 v2, v191, v197
	v_mul_f32_e32 v2, 0x3fb8aa3b, v2
	v_exp_f32_e32 v2, v2
	v_sub_f32_e32 v0, v0, v197
	v_mul_f32_e32 v0, 0x3fb8aa3b, v0
	v_exp_f32_e32 v0, v0
	v_add_f32_e32 v5, v3, v2
	v_sub_f32_e32 v3, v7, v197
	v_mul_f32_e32 v3, 0x3fb8aa3b, v3
	v_exp_f32_e32 v3, v3
	v_cvt_pk_bf16_f32 v70, v70, v71
	v_cvt_pk_bf16_f32 v71, v72, v73
	v_cvt_pk_bf16_f32 v72, v66, v67
	v_add_f32_e32 v7, v5, v3
	v_sub_f32_e32 v5, v193, v197
	v_mul_f32_e32 v5, 0x3fb8aa3b, v5
	v_exp_f32_e32 v5, v5
	v_add_u32_e32 v66, v115, v114
	v_add_u32_e32 v66, 0xd800, v66
	v_cvt_pk_bf16_f32 v73, v68, v69
	v_add_f32_e32 v12, v7, v5
	v_sub_f32_e32 v7, v195, v197
	v_mul_f32_e32 v7, 0x3fb8aa3b, v7
	v_exp_f32_e32 v7, v7
	ds_read2_b64 v[66:69], v66 offset1:4
	s_waitcnt lgkmcnt(0)
	v_mfma_f32_16x16x32_bf16 v[66:69], v[66:69], v[70:73], 0
	v_add_f32_e32 v15, v12, v7
	v_sub_f32_e32 v12, v194, v197
	v_mul_f32_e32 v12, 0x3fb8aa3b, v12
	v_exp_f32_e32 v12, v12
	s_nop 0
	v_add_f32_e32 v20, v15, v12
	v_sub_f32_e32 v15, v196, v197
	v_mul_f32_e32 v15, 0x3fb8aa3b, v15
	v_exp_f32_e32 v15, v15
	s_nop 0
	v_add_f32_e32 v24, v20, v15
	v_sub_f32_e32 v20, v198, v197
	v_mul_f32_e32 v20, 0x3fb8aa3b, v20
	v_exp_f32_e32 v20, v20
	s_nop 0
	v_add_f32_e32 v151, v24, v20
	v_sub_f32_e32 v24, v199, v197
	v_mul_f32_e32 v24, 0x3fb8aa3b, v24
	v_exp_f32_e32 v24, v24
	s_nop 0
	v_add_f32_e32 v151, v151, v24
	ds_bpermute_b32 v101, v101, v151
	s_waitcnt lgkmcnt(0)
	v_add_f32_e32 v101, v151, v101
	ds_bpermute_b32 v151, v155, v101
	s_waitcnt lgkmcnt(0)
	v_add_f32_e32 v101, v101, v151
	v_add_f32_e32 v0, v0, v101
	v_add_u32_e32 v101, v115, v116
	v_add_u32_e32 v101, 0xd800, v101
	ds_read2_b64 v[156:159], v101 offset1:4
	v_add_u32_e32 v101, v115, v117
	v_add_u32_e32 v101, 0xd800, v101
	ds_read2_b64 v[180:183], v101 offset1:4
	v_add_u32_e32 v101, v115, v118
	v_add_u32_e32 v101, 0xd800, v101
	ds_read2_b64 v[184:187], v101 offset1:4
	s_waitcnt lgkmcnt(2)
	v_mfma_f32_16x16x32_bf16 v[156:159], v[156:159], v[70:73], 0
	s_waitcnt lgkmcnt(1)
	v_mfma_f32_16x16x32_bf16 v[180:183], v[180:183], v[70:73], 0
	s_waitcnt lgkmcnt(0)
	v_mfma_f32_16x16x32_bf16 v[70:73], v[184:187], v[70:73], 0
	v_cvt_pk_bf16_f32 v62, v62, v63
	v_cvt_pk_bf16_f32 v63, v64, v65
	v_cvt_pk_bf16_f32 v64, v58, v59
	v_add_u32_e32 v58, v119, v114
	v_add_u32_e32 v58, 0xd800, v58
	v_cvt_pk_bf16_f32 v65, v60, v61
	ds_read2_b64 v[58:61], v58 offset1:4
	v_add_u32_e32 v101, v119, v117
	v_add_u32_e32 v101, 0xd800, v101
	s_waitcnt lgkmcnt(0)
	v_mfma_f32_16x16x32_bf16 v[58:61], v[58:61], v[62:65], v[66:69]
	s_nop 2
	v_add_u32_e32 v66, v119, v116
	v_add_u32_e32 v66, 0xd800, v66
	ds_read2_b64 v[66:69], v66 offset1:4
	s_waitcnt lgkmcnt(0)
	v_mfma_f32_16x16x32_bf16 v[66:69], v[66:69], v[62:65], v[156:159]
	s_nop 2
	ds_read2_b64 v[156:159], v101 offset1:4
	v_add_u32_e32 v101, v119, v118
	v_add_u32_e32 v101, 0xd800, v101
	s_waitcnt lgkmcnt(0)
	v_mfma_f32_16x16x32_bf16 v[156:159], v[156:159], v[62:65], v[180:183]
	s_nop 2
	ds_read2_b64 v[180:183], v101 offset1:4
	s_waitcnt lgkmcnt(0)
	v_mfma_f32_16x16x32_bf16 v[62:65], v[180:183], v[62:65], v[70:73]
	s_nop 2
	v_cvt_pk_bf16_f32 v70, v35, v39
	v_add_u32_e32 v35, v120, v114
	v_add_u32_e32 v35, 0xd800, v35
	v_cvt_pk_bf16_f32 v71, v54, v55
	v_cvt_pk_bf16_f32 v72, v50, v56
	v_cvt_pk_bf16_f32 v73, v57, v53
	ds_read2_b64 v[54:57], v35 offset1:4
	v_add_u32_e32 v35, v120, v116
	v_add_u32_e32 v35, 0xd800, v35
	s_waitcnt lgkmcnt(0)
	v_mfma_f32_16x16x32_bf16 v[54:57], v[54:57], v[70:73], v[58:61]
	s_nop 2
	ds_read2_b64 v[58:61], v35 offset1:4
	v_add_u32_e32 v35, v120, v117
	v_add_u32_e32 v35, 0xd800, v35
	s_waitcnt lgkmcnt(0)
	v_mfma_f32_16x16x32_bf16 v[58:61], v[58:61], v[70:73], v[66:69]
	s_nop 2
	ds_read2_b64 v[66:69], v35 offset1:4
	v_add_u32_e32 v35, v120, v118
	v_add_u32_e32 v35, 0xd800, v35
	s_waitcnt lgkmcnt(0)
	v_mfma_f32_16x16x32_bf16 v[66:69], v[66:69], v[70:73], v[156:159]
	s_nop 2
	ds_read2_b64 v[156:159], v35 offset1:4
	s_waitcnt lgkmcnt(0)
; __device__ __forceinline__ uint2 pack4(float a, float b, float c, float d) { return make_uint2(pack2(a, b), pack2(c, d)); }
; __global__ void __launch_bounds__(NTHREADS, 2) fwd_megakernel(Params p_arg) {
;     ...
; #pragma unroll
;           for (int pp = 0; pp < 9; ++pp) {
;             union { bf16x8 v; uint32_t u[4]; } pf;
;             pf.u[0] = pack2(S[2*pp][0], S[2*pp][1]); pf.u[1] = pack2(S[2*pp][2], S[2*pp][3]);
;             pf.u[2] = pack2(S[2*pp+1][0], S[2*pp+1][1]); pf.u[3] = pack2(S[2*pp+1][2], S[2*pp+1][3]);
; #pragma unroll
;             for (int dt = 0; dt < 4; ++dt) {
;               union { bf16x8 v; uint2 h2[2]; } vfr;
;               const u16* vb = VT + (dt * 16 + fr) * 392 + (kt0 + 2 * pp) * 16 + fq * 4;
;               vfr.h2[0] = *(const uint2*)(vb);
;               vfr.h2[1] = *(const uint2*)(vb + 16);
;               O[dt] = __builtin_amdgcn_mfma_f32_16x16x32_bf16(vfr.v, pf.v, O[dt], 0, 0, 0);
;             }
;             __builtin_amdgcn_sched_barrier(0);
;           }
; #pragma unroll
;           for (int dp = 0; dp < 2; ++dp)
;             store_pair16(ABp + tokq * 1024 + 512 + h * 64 + dp * 32, fq,
;                          pack4(O[2*dp][0] * inv, O[2*dp][1] * inv, O[2*dp][2] * inv, O[2*dp][3] * inv),
;                          pack4(O[2*dp+1][0] * inv, O[2*dp+1][1] * inv, O[2*dp+1][2] * inv, O[2*dp+1][3] * inv));
;         }
;         __syncthreads();
;       }
;     ...
;     }
	v_mfma_f32_16x16x32_bf16 v[62:65], v[156:159], v[70:73], v[62:65]
	v_cvt_pk_bf16_f32 v70, v27, v31
	v_add_u32_e32 v27, v121, v114
	v_add_u32_e32 v27, 0xd800, v27
	v_cvt_pk_bf16_f32 v73, v51, v52
	ds_read2_b64 v[50:53], v27 offset1:4
	v_add_u32_e32 v27, v121, v116
	v_cvt_pk_bf16_f32 v71, v37, v41
	v_cvt_pk_bf16_f32 v72, v46, v48
	v_add_u32_e32 v27, 0xd800, v27
	s_waitcnt lgkmcnt(0)
	v_mfma_f32_16x16x32_bf16 v[50:53], v[50:53], v[70:73], v[54:57]
	s_nop 2
	ds_read2_b64 v[54:57], v27 offset1:4
	v_add_u32_e32 v27, v121, v117
	v_add_u32_e32 v27, 0xd800, v27
	s_waitcnt lgkmcnt(0)
	v_mfma_f32_16x16x32_bf16 v[54:57], v[54:57], v[70:73], v[58:61]
	s_nop 2
	ds_read2_b64 v[58:61], v27 offset1:4
	v_add_u32_e32 v27, v121, v118
	v_add_u32_e32 v27, 0xd800, v27
	s_waitcnt lgkmcnt(0)
	v_mfma_f32_16x16x32_bf16 v[58:61], v[58:61], v[70:73], v[66:69]
	s_nop 2
	ds_read2_b64 v[66:69], v27 offset1:4
	s_waitcnt lgkmcnt(0)
	v_mfma_f32_16x16x32_bf16 v[62:65], v[66:69], v[70:73], v[62:65]
	v_cvt_pk_bf16_f32 v66, v19, v23
	v_add_u32_e32 v19, v122, v114
	v_add_u32_e32 v19, 0xd800, v19
	v_cvt_pk_bf16_f32 v69, v47, v49
	ds_read2_b64 v[46:49], v19 offset1:4
	v_add_u32_e32 v19, v122, v116
	v_cvt_pk_bf16_f32 v67, v29, v33
	v_cvt_pk_bf16_f32 v68, v42, v44
	v_add_u32_e32 v19, 0xd800, v19
	s_waitcnt lgkmcnt(0)
	v_mfma_f32_16x16x32_bf16 v[46:49], v[46:49], v[66:69], v[50:53]
	s_nop 2
	ds_read2_b64 v[50:53], v19 offset1:4
	v_add_u32_e32 v19, v122, v117
	v_add_u32_e32 v19, 0xd800, v19
	s_waitcnt lgkmcnt(0)
	v_mfma_f32_16x16x32_bf16 v[50:53], v[50:53], v[66:69], v[54:57]
	s_nop 2
	ds_read2_b64 v[54:57], v19 offset1:4
	v_add_u32_e32 v19, v122, v118
	v_add_u32_e32 v19, 0xd800, v19
	s_waitcnt lgkmcnt(0)
	v_mfma_f32_16x16x32_bf16 v[54:57], v[54:57], v[66:69], v[58:61]
	s_nop 2
	ds_read2_b64 v[58:61], v19 offset1:4
	s_waitcnt lgkmcnt(0)
	v_mfma_f32_16x16x32_bf16 v[58:61], v[58:61], v[66:69], v[62:65]
	s_nop 2
	v_cvt_pk_bf16_f32 v62, v13, v16
	v_add_u32_e32 v13, v123, v114
	v_add_u32_e32 v13, 0xd800, v13
	v_cvt_pk_bf16_f32 v65, v43, v45
	ds_read2_b64 v[42:45], v13 offset1:4
	v_add_u32_e32 v13, v123, v116
	v_cvt_pk_bf16_f32 v63, v21, v25
	v_cvt_pk_bf16_f32 v64, v34, v38
	v_add_u32_e32 v13, 0xd800, v13
	s_waitcnt lgkmcnt(0)
	v_mfma_f32_16x16x32_bf16 v[42:45], v[42:45], v[62:65], v[46:49]
	s_nop 2
	ds_read2_b64 v[46:49], v13 offset1:4
	v_add_u32_e32 v13, v123, v117
	v_add_u32_e32 v13, 0xd800, v13
	s_waitcnt lgkmcnt(0)
	v_mfma_f32_16x16x32_bf16 v[46:49], v[46:49], v[62:65], v[50:53]
	s_nop 2
	ds_read2_b64 v[50:53], v13 offset1:4
	v_add_u32_e32 v13, v123, v118
	v_add_u32_e32 v13, 0xd800, v13
	s_waitcnt lgkmcnt(0)
	v_mfma_f32_16x16x32_bf16 v[50:53], v[50:53], v[62:65], v[54:57]
	s_nop 2
	ds_read2_b64 v[54:57], v13 offset1:4
	s_waitcnt lgkmcnt(0)
	v_mfma_f32_16x16x32_bf16 v[54:57], v[54:57], v[62:65], v[58:61]
	s_nop 2
	v_cvt_pk_bf16_f32 v58, v8, v10
	v_add_u32_e32 v8, v124, v114
	v_add_u32_e32 v8, 0xd800, v8
	v_cvt_pk_bf16_f32 v61, v36, v40
	ds_read2_b64 v[34:37], v8 offset1:4
	v_add_u32_e32 v8, v124, v116
	v_add_u32_e32 v8, 0xd800, v8
	ds_read2_b64 v[38:41], v8 offset1:4
	v_add_u32_e32 v8, v124, v117
	v_cvt_pk_bf16_f32 v59, v14, v17
	v_cvt_pk_bf16_f32 v60, v26, v30
	v_add_u32_e32 v8, 0xd800, v8
	s_waitcnt lgkmcnt(1)
	v_mfma_f32_16x16x32_bf16 v[34:37], v[34:37], v[58:61], v[42:45]
	s_nop 2
	ds_read2_b64 v[42:45], v8 offset1:4
	v_add_u32_e32 v8, v124, v118
	v_add_u32_e32 v8, 0xd800, v8
	s_waitcnt lgkmcnt(1)
	v_mfma_f32_16x16x32_bf16 v[38:41], v[38:41], v[58:61], v[46:49]
	s_nop 2
	ds_read2_b64 v[46:49], v8 offset1:4
	s_waitcnt lgkmcnt(1)
	v_mfma_f32_16x16x32_bf16 v[42:45], v[42:45], v[58:61], v[50:53]
	s_waitcnt lgkmcnt(0)
	v_mfma_f32_16x16x32_bf16 v[46:49], v[46:49], v[58:61], v[54:57]
	v_cvt_pk_bf16_f32 v8, v4, v6
	v_add_u32_e32 v4, v125, v114
	v_add_u32_e32 v4, 0xd800, v4
	v_cvt_pk_bf16_f32 v10, v18, v22
	ds_read2_b64 v[16:19], v4 offset1:4
	v_add_u32_e32 v4, v125, v116
	v_add_u32_e32 v4, 0xd800, v4
	v_cvt_pk_bf16_f32 v9, v9, v11
	v_cvt_pk_bf16_f32 v11, v28, v32
	ds_read2_b64 v[26:29], v4 offset1:4
	v_add_u32_e32 v4, v125, v117
	v_add_u32_e32 v4, 0xd800, v4
	ds_read2_b64 v[30:33], v4 offset1:4
	v_add_u32_e32 v4, v125, v118
	v_add_u32_e32 v4, 0xd800, v4
	s_waitcnt lgkmcnt(2)
	v_mfma_f32_16x16x32_bf16 v[16:19], v[16:19], v[8:11], v[34:37]
	s_nop 2
	ds_read2_b64 v[34:37], v4 offset1:4
	s_waitcnt lgkmcnt(2)
	v_mfma_f32_16x16x32_bf16 v[26:29], v[26:29], v[8:11], v[38:41]
	s_waitcnt lgkmcnt(1)
	v_mfma_f32_16x16x32_bf16 v[30:33], v[30:33], v[8:11], v[42:45]
	s_waitcnt lgkmcnt(0)
	v_mfma_f32_16x16x32_bf16 v[8:11], v[34:37], v[8:11], v[46:49]
	v_add_u32_e32 v6, v126, v114
	v_add_u32_e32 v6, 0xd800, v6
	v_cvt_pk_bf16_f32 v4, v12, v15
	ds_read2_b64 v[12:15], v6 offset1:4
	v_add_u32_e32 v6, v126, v116
	v_cvt_pk_bf16_f32 v2, v2, v3
	v_cvt_pk_bf16_f32 v3, v5, v7
	v_cvt_pk_bf16_f32 v5, v20, v24
	v_add_u32_e32 v6, 0xd800, v6
	s_waitcnt lgkmcnt(0)
	v_mfma_f32_16x16x32_bf16 v[12:15], v[12:15], v[2:5], v[16:19]
	s_nop 2
	ds_read2_b64 v[16:19], v6 offset1:4
	v_add_u32_e32 v6, v126, v117
	v_add_u32_e32 v6, 0xd800, v6
	ds_read2_b64 v[20:23], v6 offset1:4
	v_add_u32_e32 v6, v126, v118
	v_add_u32_e32 v6, 0xd800, v6
	s_waitcnt lgkmcnt(1)
	v_mfma_f32_16x16x32_bf16 v[16:19], v[16:19], v[2:5], v[26:29]
	s_nop 2
	ds_read2_b64 v[24:27], v6 offset1:4
	s_waitcnt lgkmcnt(1)
	v_mfma_f32_16x16x32_bf16 v[20:23], v[20:23], v[2:5], v[30:33]
	s_waitcnt lgkmcnt(0)
	v_mfma_f32_16x16x32_bf16 v[2:5], v[24:27], v[2:5], v[8:11]
	v_rcp_f32_e32 v0, v0
	s_nop 1
	v_lshl_add_u64 v[10:11], v[110:111], 0, s[24:25]
	s_add_u32 s24, s24, 0x80
	s_addc_u32 s25, s25, 0
	s_add_i32 s0, s0, 1
	s_add_u32 s12, s12, 4
	v_pk_mul_f32 v[6:7], v[0:1], v[12:13] op_sel_hi:[0,1]
	v_pk_mul_f32 v[8:9], v[0:1], v[14:15] op_sel_hi:[0,1]
	v_pk_mul_f32 v[12:13], v[0:1], v[16:17] op_sel_hi:[0,1]
	v_pk_mul_f32 v[14:15], v[0:1], v[18:19] op_sel_hi:[0,1]
	s_addc_u32 s13, s13, 0
	v_pk_mul_f32 v[16:17], v[0:1], v[20:21] op_sel_hi:[0,1]
	v_pk_mul_f32 v[18:19], v[0:1], v[22:23] op_sel_hi:[0,1]
	v_pk_mul_f32 v[20:21], v[0:1], v[2:3] op_sel_hi:[0,1]
	v_pk_mul_f32 v[22:23], v[0:1], v[4:5] op_sel_hi:[0,1]
	v_cvt_pk_bf16_f32 v2, v6, v7
	v_cvt_pk_bf16_f32 v3, v8, v9
	v_cvt_pk_bf16_f32 v4, v12, v13
	v_cvt_pk_bf16_f32 v5, v14, v15
	s_cmpk_eq_i32 s24, 0x200
	v_cvt_pk_bf16_f32 v6, v16, v17
	v_cvt_pk_bf16_f32 v7, v18, v19
	v_cvt_pk_bf16_f32 v8, v20, v21
	v_cvt_pk_bf16_f32 v9, v22, v23
	v_permlane16_swap_b32_e32 v2, v4
	v_permlane16_swap_b32_e32 v3, v5
	v_permlane16_swap_b32_e32 v6, v8
	v_permlane16_swap_b32_e32 v7, v9
	global_store_dwordx4 v[10:11], v[2:5], off offset:-64
	global_store_dwordx4 v[10:11], v[6:9], off
	s_cbranch_scc0 .LBB0_312
	s_mov_b32 s28, 1
	s_mov_b64 s[12:13], 0
	s_and_b64 vcc, exec, s[92:93]
	s_barrier
	s_cbranch_vccz .LBB0_299
	s_add_i32 s99, s99, s3
	s_add_i32 s98, s98, s3
	s_cmpk_gt_i32 s99, 0xff
	s_cbranch_scc0 .LBB0_294

.LBB0_530:
	s_ashr_i32 s5, s4, 31
	s_lshl_b64 s[0:1], s[4:5], 19
	v_lshl_add_u64 v[24:25], v[20:21], 0, s[0:1]
	s_lshl_b64 s[0:1], s[4:5], 18
	v_lshl_add_u64 v[26:27], v[22:23], 0, s[0:1]
	s_ashr_i32 s0, s4, 5
	s_mul_hi_i32 s1, s0, 0x6000
	s_mulk_i32 s0, 0x6000
	s_add_u32 s0, s10, s0
	s_addc_u32 s1, s11, s1
	s_add_u32 s6, s0, 0x4000
	s_addc_u32 s7, s1, 0
	s_add_u32 s0, s0, 0x3000
	s_addc_u32 s1, s1, 0
	global_load_dwordx4 v[28:31], v[18:19], off
	global_load_dwordx4 v[82:85], v0, s[6:7]
	global_load_dwordx4 v[2:5], v0, s[0:1]
	global_load_dwordx4 v[32:35], v[18:19], off offset:1024
	global_load_dwordx4 v[86:89], v50, s[6:7]
	global_load_dwordx4 v[6:9], v0, s[0:1] offset:1024
	global_load_dwordx4 v[36:39], v[18:19], off offset:2048
	global_load_dwordx4 v[90:93], v51, s[6:7]
	global_load_dwordx4 v[10:13], v0, s[0:1] offset:2048
	global_load_dwordx4 v[40:43], v[18:19], off offset:3072
	global_load_dwordx4 v[94:97], v52, s[6:7]
	global_load_dwordx4 v[14:17], v0, s[0:1] offset:3072
	global_load_dwordx4 v[54:57], v[24:25], off offset:-2048
	global_load_dwordx4 v[58:61], v[24:25], off offset:-1024
	global_load_dwordx4 v[62:65], v[24:25], off
	global_load_dwordx4 v[66:69], v[24:25], off offset:1024
	s_mov_b64 s[6:7], 0
	s_waitcnt vmcnt(4)
	v_pk_add_f32 v[82:83], v[82:83], 1.0 op_sel_hi:[1,0]
	v_pk_add_f32 v[84:85], v[84:85], 1.0 op_sel_hi:[1,0]
	v_pk_add_f32 v[86:87], v[86:87], 1.0 op_sel_hi:[1,0]
	v_pk_add_f32 v[88:89], v[88:89], 1.0 op_sel_hi:[1,0]
	v_pk_add_f32 v[90:91], v[90:91], 1.0 op_sel_hi:[1,0]
	v_pk_add_f32 v[92:93], v[92:93], 1.0 op_sel_hi:[1,0]
	v_pk_add_f32 v[94:95], v[94:95], 1.0 op_sel_hi:[1,0]
	v_pk_add_f32 v[96:97], v[96:97], 1.0 op_sel_hi:[1,0]
	v_pk_mul_f32 v[28:29], v[28:29], v[82:83]
	v_pk_mul_f32 v[30:31], v[30:31], v[84:85]
	v_pk_mul_f32 v[32:33], v[32:33], v[86:87]
	v_pk_mul_f32 v[34:35], v[34:35], v[88:89]
	v_pk_mul_f32 v[36:37], v[36:37], v[90:91]
	v_pk_mul_f32 v[38:39], v[38:39], v[92:93]
	v_pk_mul_f32 v[40:41], v[40:41], v[94:95]
	v_pk_mul_f32 v[42:43], v[42:43], v[96:97]
